# hoist 16 residual-tile loads to epilogue start in EpiResid/ResidK/ResidFinal (counted vmcnt)
# speedup vs baseline: 1.0007x; 1.0007x over previous
; #define PG8_LAS __attribute__((address_space(3)))
; __device__ __forceinline__ unsigned cvt_pk_bf16(float lo, float hi) { unsigned r; asm volatile("v_cvt_pk_bf16_f32 %0, %1, %2" : "=v"(r) : "v"(lo), "v"(hi)); return r; }
; #define PG8_WAIT_V(n) asm volatile("s_waitcnt vmcnt(" #n ")" ::: "memory")
; #define PG8_BAR __builtin_amdgcn_s_barrier()
;     __device__ __forceinline__ void fused(f32x4 (&acc)[2][2][4][2], const Unit& u, int wr, int wc, int fr, int fq, PG8_LAS unsigned char* lds, int wid, int lane) const {
;         PG8_LAS float* P = (PG8_LAS float*)lds;
;         const int col0 = u.pn * BM + wc * 32 + 8 * fq;
; #pragma unroll
;         for (int ai = 0; ai < 2; ++ai)
; #pragma unroll
;             for (int m = 0; m < 4; ++m) { const int rl = ai * HALF + wr * 64 + m * 16 + fr; const size_t off = (size_t)(u.pm * BM + rl) * ldc + col0; float q = 0.f;
; #pragma unroll
;                 for (int bj = 0; bj < 2; ++bj) { const u32x4 hb = *(const u32x4*)(xb + off + bj * HALF);
;                     const f32x4 b0 = (f32x4){__uint_as_float(hb.x << 16), __uint_as_float(hb.x & 0xffff0000u), __uint_as_float(hb.y << 16), __uint_as_float(hb.y & 0xffff0000u)};
;                     const f32x4 b1 = (f32x4){__uint_as_float(hb.z << 16), __uint_as_float(hb.z & 0xffff0000u), __uint_as_float(hb.w << 16), __uint_as_float(hb.w & 0xffff0000u)};
;                     const f32x4 v0 = b0 + acc[ai][bj][m][0], v1 = b1 + acc[ai][bj][m][1];
;                     u32x4 w; w.x = cvt_pk_bf16(v0[0], v0[1]); w.y = cvt_pk_bf16(v0[2], v0[3]); w.z = cvt_pk_bf16(v1[0], v1[1]); w.w = cvt_pk_bf16(v1[2], v1[3]);
;                     *(u32x4*)(xb + off + bj * HALF) = w;
;                     q += (v0[0] * v0[0] + v0[1] * v0[1]) + (v0[2] * v0[2] + v0[3] * v0[3]) + (v1[0] * v1[0] + v1[1] * v1[1]) + (v1[2] * v1[2] + v1[3] * v1[3]); }
;                 q += __shfl_xor(q, 16); q += __shfl_xor(q, 32);
;                 if (fq == 0) P[rl * 4 + wc] = q; }
; template <class Epi, class Sched, bool ALIGN_EPI = false, bool SP2 = false>
; __device__ __forceinline__ void gemm_phase(PG8_LAS unsigned char* lds, const Gemm g, const Sched& S, const Epi& E) {
;     ...
;     PG8_WAIT_V(0);
;     if constexpr (!ALIGN_EPI) { if (wr == 0) PG8_BAR; }
;     PG8_BAR;
.LBB0_205:
	s_lshl_b32 s2, s43, 5
	s_lshl_b32 s3, s0, 8
	s_or_b32 s2, s3, s2
	s_lshl_b32 s3, s44, 8
	v_lshrrev_b32_e32 v180, 1, v149
	v_and_or_b32 v180, v180, 24, s2
	v_add_u32_e32 v181, s3, v148
	v_lshlrev_b32_e32 v181, 12, v181
	v_lshl_add_u32 v181, v180, 1, v181
	v_readlane_b32 s2, v252, 36
	v_readlane_b32 s3, v252, 37
	s_nop 4
	global_load_dwordx4 v[152:155], v181, s[2:3]
	global_load_dwordx4 v[156:159], v181, s[2:3] offset:256
	v_add_u32_e32 v181, 0x10000, v181
	global_load_dwordx4 v[160:163], v181, s[2:3]
	global_load_dwordx4 v[164:167], v181, s[2:3] offset:256
	v_add_u32_e32 v181, 0x10000, v181
	global_load_dwordx4 v[168:171], v181, s[2:3]
	global_load_dwordx4 v[172:175], v181, s[2:3] offset:256
	v_add_u32_e32 v181, 0x10000, v181
	global_load_dwordx4 v[176:179], v181, s[2:3]
	global_load_dwordx4 v[184:187], v181, s[2:3] offset:256
	v_add_u32_e32 v181, 0x50000, v181
	global_load_dwordx4 v[188:191], v181, s[2:3]
	global_load_dwordx4 v[192:195], v181, s[2:3] offset:256
	v_add_u32_e32 v181, 0x10000, v181
	global_load_dwordx4 v[196:199], v181, s[2:3]
	global_load_dwordx4 v[200:203], v181, s[2:3] offset:256
	v_add_u32_e32 v181, 0x10000, v181
	global_load_dwordx4 v[204:207], v181, s[2:3]
	global_load_dwordx4 v[224:227], v181, s[2:3] offset:256
	v_add_u32_e32 v181, 0x10000, v181
	global_load_dwordx4 v[228:231], v181, s[2:3]
	global_load_dwordx4 v[232:235], v181, s[2:3] offset:256
	s_waitcnt vmcnt(16)
	s_cmpk_gt_u32 s1, 0xff
	s_cbranch_scc1 .LBB0_207
	s_barrier
.LBB0_207:
	s_lshl_b32 s2, s43, 5
	s_lshl_b32 s3, s0, 8
	s_lshl_b32 s4, s44, 8
	v_lshrrev_b32_e32 v0, 1, v149
	s_or_b32 s2, s3, s2
	v_add_u32_e32 v136, s4, v148
	v_and_or_b32 v2, v0, 24, s2
	v_ashrrev_i32_e32 v137, 31, v136
	v_readlane_b32 s2, v252, 36
	v_lshlrev_b64 v[136:137], 12, v[136:137]
	v_readlane_b32 s3, v252, 37
	v_ashrrev_i32_e32 v3, 31, v2
	s_barrier
	v_lshl_add_u64 v[136:137], s[2:3], 0, v[136:137]
	v_lshl_add_u64 v[140:141], v[2:3], 1, v[136:137]
	v_cmp_lt_i32_e32 vcc, v219, v214
	v_and_b32_e32 v0, 63, v149
	s_lshl_b32 s2, s43, 2
	s_add_i32 s5, s2, 0
	s_waitcnt vmcnt(15)
	v_lshlrev_b32_e32 v142, 16, v152
	v_and_b32_e32 v143, 0xffff0000, v152
	v_lshlrev_b32_e32 v136, 16, v153
	v_and_b32_e32 v137, 0xffff0000, v153
	v_lshlrev_b32_e32 v144, 16, v154
	v_and_b32_e32 v145, 0xffff0000, v154
	v_lshlrev_b32_e32 v138, 16, v155
	v_and_b32_e32 v139, 0xffff0000, v155
	v_pk_add_f32 v[146:147], v[134:135], v[136:137]
	v_pk_add_f32 v[142:143], v[132:133], v[142:143]
	v_pk_add_f32 v[138:139], v[130:131], v[138:139]
	v_pk_add_f32 v[144:145], v[128:129], v[144:145]
	v_cvt_pk_bf16_f32 v130, v142, v143
	v_cvt_pk_bf16_f32 v131, v146, v147
	v_mul_f32_e32 v143, v143, v143
	v_cvt_pk_bf16_f32 v132, v144, v145
	v_cvt_pk_bf16_f32 v133, v138, v139
	v_mul_f32_e32 v147, v147, v147
	v_mul_f32_e32 v145, v145, v145
	v_mul_f32_e32 v139, v139, v139
	v_fmac_f32_e32 v143, v142, v142
	v_fmac_f32_e32 v147, v146, v146
	v_fmac_f32_e32 v145, v144, v144
	v_fmac_f32_e32 v139, v138, v138
	v_add_f32_e32 v138, v143, v147
	v_add_f32_e32 v138, v145, v138
	v_add_f32_e32 v144, v139, v138
	v_cndmask_b32_e32 v128, v213, v219, vcc
	v_lshlrev_b32_e32 v128, 2, v128
	v_cmp_lt_i32_e32 vcc, v220, v214
	global_store_dwordx4 v[140:141], v[130:133], off
	s_waitcnt vmcnt(15)
	v_lshlrev_b32_e32 v138, 16, v156
	v_and_b32_e32 v139, 0xffff0000, v156
	v_lshlrev_b32_e32 v134, 16, v157
	v_and_b32_e32 v135, 0xffff0000, v157
	v_lshlrev_b32_e32 v142, 16, v158
	v_and_b32_e32 v143, 0xffff0000, v158
	v_lshlrev_b32_e32 v136, 16, v159
	v_and_b32_e32 v137, 0xffff0000, v159
	v_pk_add_f32 v[126:127], v[126:127], v[134:135]
	v_pk_add_f32 v[124:125], v[124:125], v[138:139]
	v_pk_add_f32 v[134:135], v[122:123], v[136:137]
	v_pk_add_f32 v[136:137], v[120:121], v[142:143]
	v_mul_f32_e32 v120, v125, v125
	v_mul_f32_e32 v121, v127, v127
	v_mul_f32_e32 v122, v137, v137
	v_fmac_f32_e32 v120, v124, v124
	v_fmac_f32_e32 v121, v126, v126
	v_mul_f32_e32 v123, v135, v135
	v_fmac_f32_e32 v122, v136, v136
	v_add_f32_e32 v120, v120, v121
	v_fmac_f32_e32 v123, v134, v134
	v_add_f32_e32 v120, v122, v120
	v_add_f32_e32 v120, v123, v120
	v_add_f32_e32 v120, v144, v120
	ds_bpermute_b32 v121, v128, v120
	v_cndmask_b32_e32 v129, v213, v220, vcc
	v_cmp_gt_u32_e32 vcc, 16, v0
	v_cvt_pk_bf16_f32 v124, v124, v125
	v_cvt_pk_bf16_f32 v125, v126, v127
	s_waitcnt lgkmcnt(0)
	v_add_f32_e32 v121, v120, v121
	v_lshlrev_b32_e32 v120, 2, v129
	ds_bpermute_b32 v122, v120, v121
	v_cvt_pk_bf16_f32 v126, v136, v137
	v_cvt_pk_bf16_f32 v127, v134, v135
	global_store_dwordx4 v[140:141], v[124:127], off offset:256
	s_and_saveexec_b64 s[2:3], vcc
	s_movk_i32 s37, 0x2000
	s_cbranch_execz .LBB0_209
	v_lshl_add_u32 v123, v148, 4, s5
	s_waitcnt lgkmcnt(0)
	v_add_f32_e32 v121, v121, v122
	ds_write_b32 v123, v121
; __device__ __forceinline__ unsigned cvt_pk_bf16(float lo, float hi) { unsigned r; asm volatile("v_cvt_pk_bf16_f32 %0, %1, %2" : "=v"(r) : "v"(lo), "v"(hi)); return r; }
;     __device__ __forceinline__ void fused(f32x4 (&acc)[2][2][4][2], const Unit& u, int wr, int wc, int fr, int fq, PG8_LAS unsigned char* lds, int wid, int lane) const {
;     ...
;         for (int ai = 0; ai < 2; ++ai)
; #pragma unroll
;             for (int m = 0; m < 4; ++m) { const int rl = ai * HALF + wr * 64 + m * 16 + fr; const size_t off = (size_t)(u.pm * BM + rl) * ldc + col0; float q = 0.f;
; #pragma unroll
;                 for (int bj = 0; bj < 2; ++bj) { const u32x4 hb = *(const u32x4*)(xb + off + bj * HALF);
;                     const f32x4 b0 = (f32x4){__uint_as_float(hb.x << 16), __uint_as_float(hb.x & 0xffff0000u), __uint_as_float(hb.y << 16), __uint_as_float(hb.y & 0xffff0000u)};
;                     const f32x4 b1 = (f32x4){__uint_as_float(hb.z << 16), __uint_as_float(hb.z & 0xffff0000u), __uint_as_float(hb.w << 16), __uint_as_float(hb.w & 0xffff0000u)};
;                     const f32x4 v0 = b0 + acc[ai][bj][m][0], v1 = b1 + acc[ai][bj][m][1];
;                     u32x4 w; w.x = cvt_pk_bf16(v0[0], v0[1]); w.y = cvt_pk_bf16(v0[2], v0[3]); w.z = cvt_pk_bf16(v1[0], v1[1]); w.w = cvt_pk_bf16(v1[2], v1[3]);
;                     *(u32x4*)(xb + off + bj * HALF) = w;
;                     q += (v0[0] * v0[0] + v0[1] * v0[1]) + (v0[2] * v0[2] + v0[3] * v0[3]) + (v1[0] * v1[0] + v1[1] * v1[1]) + (v1[2] * v1[2] + v1[3] * v1[3]); }
;                 q += __shfl_xor(q, 16); q += __shfl_xor(q, 32);
;                 if (fq == 0) P[rl * 4 + wc] = q; }
.LBB0_209:
	s_or_b64 exec, exec, s[2:3]
	v_or_b32_e32 v121, 16, v148
	s_waitcnt lgkmcnt(0)
	v_add_u32_e32 v122, s4, v121
	v_ashrrev_i32_e32 v123, 31, v122
	v_readlane_b32 s2, v252, 36
	v_lshlrev_b64 v[122:123], 12, v[122:123]
	v_readlane_b32 s3, v252, 37
	s_nop 1
	v_lshl_add_u64 v[122:123], s[2:3], 0, v[122:123]
	v_lshl_add_u64 v[126:127], v[2:3], 1, v[122:123]
	s_waitcnt vmcnt(15)
	v_lshlrev_b32_e32 v130, 16, v160
	v_and_b32_e32 v131, 0xffff0000, v160
	v_lshlrev_b32_e32 v122, 16, v161
	v_and_b32_e32 v123, 0xffff0000, v161
	v_lshlrev_b32_e32 v132, 16, v162
	v_and_b32_e32 v133, 0xffff0000, v162
	v_lshlrev_b32_e32 v124, 16, v163
	v_and_b32_e32 v125, 0xffff0000, v163
	v_pk_add_f32 v[122:123], v[118:119], v[122:123]
	v_pk_add_f32 v[130:131], v[116:117], v[130:131]
	v_pk_add_f32 v[124:125], v[114:115], v[124:125]
	v_pk_add_f32 v[132:133], v[112:113], v[132:133]
	v_cvt_pk_bf16_f32 v112, v130, v131
	v_cvt_pk_bf16_f32 v113, v122, v123
	v_mul_f32_e32 v129, v131, v131
	v_cvt_pk_bf16_f32 v114, v132, v133
	v_cvt_pk_bf16_f32 v115, v124, v125
	v_mul_f32_e32 v123, v123, v123
	v_mul_f32_e32 v131, v133, v133
	v_fmac_f32_e32 v129, v130, v130
	v_fmac_f32_e32 v123, v122, v122
	v_mul_f32_e32 v125, v125, v125
	v_fmac_f32_e32 v131, v132, v132
	v_add_f32_e32 v122, v129, v123
	v_fmac_f32_e32 v125, v124, v124
	v_add_f32_e32 v122, v131, v122
	v_add_f32_e32 v129, v125, v122
	global_store_dwordx4 v[126:127], v[112:115], off
	s_waitcnt vmcnt(15)
	v_lshlrev_b32_e32 v122, 16, v164
	v_and_b32_e32 v123, 0xffff0000, v164
	v_lshlrev_b32_e32 v116, 16, v165
	v_and_b32_e32 v117, 0xffff0000, v165
	v_lshlrev_b32_e32 v124, 16, v166
	v_and_b32_e32 v125, 0xffff0000, v166
	v_lshlrev_b32_e32 v118, 16, v167
	v_and_b32_e32 v119, 0xffff0000, v167
	v_pk_add_f32 v[110:111], v[110:111], v[116:117]
	v_pk_add_f32 v[108:109], v[108:109], v[122:123]
	v_pk_add_f32 v[116:117], v[106:107], v[118:119]
	v_pk_add_f32 v[118:119], v[104:105], v[124:125]
	v_mul_f32_e32 v104, v109, v109
	v_mul_f32_e32 v105, v111, v111
	v_mul_f32_e32 v106, v119, v119
	v_fmac_f32_e32 v104, v108, v108
	v_fmac_f32_e32 v105, v110, v110
	v_mul_f32_e32 v107, v117, v117
	v_fmac_f32_e32 v106, v118, v118
	v_add_f32_e32 v104, v104, v105
	v_add_f32_e32 v104, v106, v104
	v_fmac_f32_e32 v107, v116, v116
	v_add_f32_e32 v104, v107, v104
	v_add_f32_e32 v104, v129, v104
	ds_bpermute_b32 v105, v128, v104
	v_cvt_pk_bf16_f32 v106, v108, v109
	v_cvt_pk_bf16_f32 v107, v110, v111
	v_cvt_pk_bf16_f32 v108, v118, v119
	v_cvt_pk_bf16_f32 v109, v116, v117
	s_waitcnt lgkmcnt(0)
	v_add_f32_e32 v104, v104, v105
	ds_bpermute_b32 v105, v120, v104
	global_store_dwordx4 v[126:127], v[106:109], off offset:256
	s_and_saveexec_b64 s[2:3], vcc
	s_cbranch_execz .LBB0_211
	v_lshl_add_u32 v106, v121, 4, s5
	s_waitcnt lgkmcnt(0)
	v_add_f32_e32 v104, v104, v105
	ds_write_b32 v106, v104
.LBB0_211:
	s_or_b64 exec, exec, s[2:3]
	v_or_b32_e32 v104, 32, v148
	v_add_u32_e32 v106, s4, v104
	v_ashrrev_i32_e32 v107, 31, v106
	v_readlane_b32 s2, v252, 36
	v_lshlrev_b64 v[106:107], 12, v[106:107]
	v_readlane_b32 s3, v252, 37
	s_nop 1
	v_lshl_add_u64 v[106:107], s[2:3], 0, v[106:107]
	v_lshl_add_u64 v[110:111], v[2:3], 1, v[106:107]
	s_waitcnt vmcnt(15)
	v_lshlrev_b32_e32 v112, 16, v168
	v_and_b32_e32 v113, 0xffff0000, v168
	v_lshlrev_b32_e32 v106, 16, v169
	v_and_b32_e32 v107, 0xffff0000, v169
	v_lshlrev_b32_e32 v114, 16, v170
	v_and_b32_e32 v115, 0xffff0000, v170
	v_lshlrev_b32_e32 v108, 16, v171
	v_and_b32_e32 v109, 0xffff0000, v171
	v_pk_add_f32 v[106:107], v[102:103], v[106:107]
	v_pk_add_f32 v[112:113], v[100:101], v[112:113]
	v_pk_add_f32 v[108:109], v[98:99], v[108:109]
	v_pk_add_f32 v[114:115], v[96:97], v[114:115]
	v_cvt_pk_bf16_f32 v96, v112, v113
	v_cvt_pk_bf16_f32 v97, v106, v107
	s_waitcnt lgkmcnt(0)
	v_mul_f32_e32 v105, v113, v113
	v_cvt_pk_bf16_f32 v98, v114, v115
	v_cvt_pk_bf16_f32 v99, v108, v109
	v_mul_f32_e32 v107, v107, v107
	v_mul_f32_e32 v113, v115, v115
	v_fmac_f32_e32 v105, v112, v112
	v_fmac_f32_e32 v107, v106, v106
	v_mul_f32_e32 v109, v109, v109
	v_fmac_f32_e32 v113, v114, v114
	v_add_f32_e32 v105, v105, v107
	v_fmac_f32_e32 v109, v108, v108
	v_add_f32_e32 v105, v113, v105
	v_add_f32_e32 v105, v109, v105
	global_store_dwordx4 v[110:111], v[96:99], off
	s_waitcnt vmcnt(15)
	v_lshlrev_b32_e32 v106, 16, v172
	v_and_b32_e32 v107, 0xffff0000, v172
	v_lshlrev_b32_e32 v100, 16, v173
	v_and_b32_e32 v101, 0xffff0000, v173
	v_lshlrev_b32_e32 v108, 16, v174
	v_and_b32_e32 v109, 0xffff0000, v174
	v_lshlrev_b32_e32 v102, 16, v175
	v_and_b32_e32 v103, 0xffff0000, v175
	v_pk_add_f32 v[94:95], v[94:95], v[100:101]
	v_pk_add_f32 v[92:93], v[92:93], v[106:107]
	v_pk_add_f32 v[100:101], v[90:91], v[102:103]
	v_pk_add_f32 v[102:103], v[88:89], v[108:109]
	v_mul_f32_e32 v88, v93, v93
	v_mul_f32_e32 v89, v95, v95
	v_mul_f32_e32 v90, v103, v103
	v_fmac_f32_e32 v88, v92, v92
	v_fmac_f32_e32 v89, v94, v94
	v_mul_f32_e32 v91, v101, v101
	v_fmac_f32_e32 v90, v102, v102
	v_add_f32_e32 v88, v88, v89
	v_add_f32_e32 v88, v90, v88
	v_fmac_f32_e32 v91, v100, v100
	v_add_f32_e32 v88, v91, v88
	v_add_f32_e32 v88, v105, v88
	ds_bpermute_b32 v89, v128, v88
	v_cvt_pk_bf16_f32 v90, v92, v93
	v_cvt_pk_bf16_f32 v91, v94, v95
	v_cvt_pk_bf16_f32 v92, v102, v103
	v_cvt_pk_bf16_f32 v93, v100, v101
	s_waitcnt lgkmcnt(0)
	v_add_f32_e32 v88, v88, v89
	ds_bpermute_b32 v89, v120, v88
	global_store_dwordx4 v[110:111], v[90:93], off offset:256
	s_and_saveexec_b64 s[2:3], vcc
	s_cbranch_execz .LBB0_213
	v_lshl_add_u32 v90, v104, 4, s5
	s_waitcnt lgkmcnt(0)
	v_add_f32_e32 v88, v88, v89
	ds_write_b32 v90, v88
; __device__ __forceinline__ unsigned cvt_pk_bf16(float lo, float hi) { unsigned r; asm volatile("v_cvt_pk_bf16_f32 %0, %1, %2" : "=v"(r) : "v"(lo), "v"(hi)); return r; }
;     __device__ __forceinline__ void fused(f32x4 (&acc)[2][2][4][2], const Unit& u, int wr, int wc, int fr, int fq, PG8_LAS unsigned char* lds, int wid, int lane) const {
;     ...
;         for (int ai = 0; ai < 2; ++ai)
; #pragma unroll
;             for (int m = 0; m < 4; ++m) { const int rl = ai * HALF + wr * 64 + m * 16 + fr; const size_t off = (size_t)(u.pm * BM + rl) * ldc + col0; float q = 0.f;
; #pragma unroll
;                 for (int bj = 0; bj < 2; ++bj) { const u32x4 hb = *(const u32x4*)(xb + off + bj * HALF);
;                     const f32x4 b0 = (f32x4){__uint_as_float(hb.x << 16), __uint_as_float(hb.x & 0xffff0000u), __uint_as_float(hb.y << 16), __uint_as_float(hb.y & 0xffff0000u)};
;                     const f32x4 b1 = (f32x4){__uint_as_float(hb.z << 16), __uint_as_float(hb.z & 0xffff0000u), __uint_as_float(hb.w << 16), __uint_as_float(hb.w & 0xffff0000u)};
;                     const f32x4 v0 = b0 + acc[ai][bj][m][0], v1 = b1 + acc[ai][bj][m][1];
;                     u32x4 w; w.x = cvt_pk_bf16(v0[0], v0[1]); w.y = cvt_pk_bf16(v0[2], v0[3]); w.z = cvt_pk_bf16(v1[0], v1[1]); w.w = cvt_pk_bf16(v1[2], v1[3]);
;                     *(u32x4*)(xb + off + bj * HALF) = w;
;                     q += (v0[0] * v0[0] + v0[1] * v0[1]) + (v0[2] * v0[2] + v0[3] * v0[3]) + (v1[0] * v1[0] + v1[1] * v1[1]) + (v1[2] * v1[2] + v1[3] * v1[3]); }
;                 q += __shfl_xor(q, 16); q += __shfl_xor(q, 32);
;                 if (fq == 0) P[rl * 4 + wc] = q; }
.LBB0_213:
	s_or_b64 exec, exec, s[2:3]
	v_or_b32_e32 v88, 48, v148
	v_add_u32_e32 v90, s4, v88
	v_ashrrev_i32_e32 v91, 31, v90
	v_readlane_b32 s2, v252, 36
	v_lshlrev_b64 v[90:91], 12, v[90:91]
	v_readlane_b32 s3, v252, 37
	s_nop 1
	v_lshl_add_u64 v[90:91], s[2:3], 0, v[90:91]
	v_lshl_add_u64 v[94:95], v[2:3], 1, v[90:91]
	s_waitcnt vmcnt(15)
	v_lshlrev_b32_e32 v96, 16, v176
	v_and_b32_e32 v97, 0xffff0000, v176
	v_lshlrev_b32_e32 v90, 16, v177
	v_and_b32_e32 v91, 0xffff0000, v177
	v_lshlrev_b32_e32 v98, 16, v178
	v_and_b32_e32 v99, 0xffff0000, v178
	v_lshlrev_b32_e32 v92, 16, v179
	v_and_b32_e32 v93, 0xffff0000, v179
	v_pk_add_f32 v[90:91], v[86:87], v[90:91]
	v_pk_add_f32 v[96:97], v[84:85], v[96:97]
	v_pk_add_f32 v[92:93], v[82:83], v[92:93]
	v_pk_add_f32 v[98:99], v[80:81], v[98:99]
	v_cvt_pk_bf16_f32 v80, v96, v97
	v_cvt_pk_bf16_f32 v81, v90, v91
	s_waitcnt lgkmcnt(0)
	v_mul_f32_e32 v89, v97, v97
	v_cvt_pk_bf16_f32 v82, v98, v99
	v_cvt_pk_bf16_f32 v83, v92, v93
	v_mul_f32_e32 v91, v91, v91
	v_mul_f32_e32 v97, v99, v99
	v_fmac_f32_e32 v89, v96, v96
	v_fmac_f32_e32 v91, v90, v90
	v_mul_f32_e32 v93, v93, v93
	v_fmac_f32_e32 v97, v98, v98
	v_add_f32_e32 v89, v89, v91
	v_fmac_f32_e32 v93, v92, v92
	v_add_f32_e32 v89, v97, v89
	v_add_f32_e32 v89, v93, v89
	global_store_dwordx4 v[94:95], v[80:83], off
	s_waitcnt vmcnt(15)
	v_lshlrev_b32_e32 v90, 16, v184
	v_and_b32_e32 v91, 0xffff0000, v184
	v_lshlrev_b32_e32 v84, 16, v185
	v_and_b32_e32 v85, 0xffff0000, v185
	v_lshlrev_b32_e32 v92, 16, v186
	v_and_b32_e32 v93, 0xffff0000, v186
	v_lshlrev_b32_e32 v86, 16, v187
	v_and_b32_e32 v87, 0xffff0000, v187
	v_pk_add_f32 v[78:79], v[78:79], v[84:85]
	v_pk_add_f32 v[76:77], v[76:77], v[90:91]
	v_pk_add_f32 v[84:85], v[74:75], v[86:87]
	v_pk_add_f32 v[86:87], v[72:73], v[92:93]
	v_mul_f32_e32 v72, v77, v77
	v_mul_f32_e32 v73, v79, v79
	v_mul_f32_e32 v74, v87, v87
	v_fmac_f32_e32 v72, v76, v76
	v_fmac_f32_e32 v73, v78, v78
	v_mul_f32_e32 v75, v85, v85
	v_fmac_f32_e32 v74, v86, v86
	v_add_f32_e32 v72, v72, v73
	v_add_f32_e32 v72, v74, v72
	v_fmac_f32_e32 v75, v84, v84
	v_add_f32_e32 v72, v75, v72
	v_add_f32_e32 v72, v89, v72
	ds_bpermute_b32 v73, v128, v72
	v_cvt_pk_bf16_f32 v74, v76, v77
	v_cvt_pk_bf16_f32 v75, v78, v79
	v_cvt_pk_bf16_f32 v76, v86, v87
	v_cvt_pk_bf16_f32 v77, v84, v85
	s_waitcnt lgkmcnt(0)
	v_add_f32_e32 v72, v72, v73
	ds_bpermute_b32 v73, v120, v72
	global_store_dwordx4 v[94:95], v[74:77], off offset:256
	s_and_saveexec_b64 s[2:3], vcc
	s_cbranch_execz .LBB0_215
	v_lshl_add_u32 v74, v88, 4, s5
	s_waitcnt lgkmcnt(0)
	v_add_f32_e32 v72, v72, v73
	ds_write_b32 v74, v72
.LBB0_215:
	s_or_b64 exec, exec, s[2:3]
	v_add_u32_e32 v72, 0x80, v148
	v_add_u32_e32 v74, s4, v72
	v_ashrrev_i32_e32 v75, 31, v74
	v_readlane_b32 s2, v252, 36
	v_lshlrev_b64 v[74:75], 12, v[74:75]
	v_readlane_b32 s3, v252, 37
	s_nop 1
	v_lshl_add_u64 v[74:75], s[2:3], 0, v[74:75]
	v_lshl_add_u64 v[78:79], v[2:3], 1, v[74:75]
	s_waitcnt vmcnt(15)
	v_lshlrev_b32_e32 v80, 16, v188
	v_and_b32_e32 v81, 0xffff0000, v188
	v_lshlrev_b32_e32 v74, 16, v189
	v_and_b32_e32 v75, 0xffff0000, v189
	v_lshlrev_b32_e32 v82, 16, v190
	v_and_b32_e32 v83, 0xffff0000, v190
	v_lshlrev_b32_e32 v76, 16, v191
	v_and_b32_e32 v77, 0xffff0000, v191
	v_pk_add_f32 v[74:75], v[70:71], v[74:75]
	v_pk_add_f32 v[80:81], v[68:69], v[80:81]
	v_pk_add_f32 v[76:77], v[66:67], v[76:77]
	v_pk_add_f32 v[82:83], v[64:65], v[82:83]
	v_cvt_pk_bf16_f32 v64, v80, v81
	v_cvt_pk_bf16_f32 v65, v74, v75
	s_waitcnt lgkmcnt(0)
	v_mul_f32_e32 v73, v81, v81
	v_cvt_pk_bf16_f32 v66, v82, v83
	v_cvt_pk_bf16_f32 v67, v76, v77
	v_mul_f32_e32 v75, v75, v75
	v_mul_f32_e32 v81, v83, v83
	v_fmac_f32_e32 v73, v80, v80
	v_fmac_f32_e32 v75, v74, v74
	v_mul_f32_e32 v77, v77, v77
	v_fmac_f32_e32 v81, v82, v82
	v_add_f32_e32 v73, v73, v75
	v_fmac_f32_e32 v77, v76, v76
	v_add_f32_e32 v73, v81, v73
	v_add_f32_e32 v73, v77, v73
	global_store_dwordx4 v[78:79], v[64:67], off
	s_waitcnt vmcnt(15)
	v_lshlrev_b32_e32 v74, 16, v192
	v_and_b32_e32 v75, 0xffff0000, v192
	v_lshlrev_b32_e32 v68, 16, v193
	v_and_b32_e32 v69, 0xffff0000, v193
	v_lshlrev_b32_e32 v76, 16, v194
	v_and_b32_e32 v77, 0xffff0000, v194
	v_lshlrev_b32_e32 v70, 16, v195
	v_and_b32_e32 v71, 0xffff0000, v195
	v_pk_add_f32 v[62:63], v[62:63], v[68:69]
	v_pk_add_f32 v[60:61], v[60:61], v[74:75]
	v_pk_add_f32 v[68:69], v[58:59], v[70:71]
	v_pk_add_f32 v[70:71], v[56:57], v[76:77]
	v_mul_f32_e32 v56, v61, v61
	v_mul_f32_e32 v57, v63, v63
	v_mul_f32_e32 v58, v71, v71
	v_fmac_f32_e32 v56, v60, v60
	v_fmac_f32_e32 v57, v62, v62
	v_mul_f32_e32 v59, v69, v69
	v_fmac_f32_e32 v58, v70, v70
	v_add_f32_e32 v56, v56, v57
	v_add_f32_e32 v56, v58, v56
	v_fmac_f32_e32 v59, v68, v68
	v_add_f32_e32 v56, v59, v56
	v_add_f32_e32 v56, v73, v56
	ds_bpermute_b32 v57, v128, v56
	v_cvt_pk_bf16_f32 v58, v60, v61
	v_cvt_pk_bf16_f32 v59, v62, v63
	v_cvt_pk_bf16_f32 v60, v70, v71
	v_cvt_pk_bf16_f32 v61, v68, v69
	s_waitcnt lgkmcnt(0)
	v_add_f32_e32 v56, v56, v57
	ds_bpermute_b32 v57, v120, v56
	global_store_dwordx4 v[78:79], v[58:61], off offset:256
	s_and_saveexec_b64 s[2:3], vcc
	s_cbranch_execz .LBB0_217
	v_lshl_add_u32 v58, v72, 4, s5
	s_waitcnt lgkmcnt(0)
	v_add_f32_e32 v56, v56, v57
	ds_write_b32 v58, v56
; __device__ __forceinline__ unsigned cvt_pk_bf16(float lo, float hi) { unsigned r; asm volatile("v_cvt_pk_bf16_f32 %0, %1, %2" : "=v"(r) : "v"(lo), "v"(hi)); return r; }
;     __device__ __forceinline__ void fused(f32x4 (&acc)[2][2][4][2], const Unit& u, int wr, int wc, int fr, int fq, PG8_LAS unsigned char* lds, int wid, int lane) const {
;     ...
;         for (int ai = 0; ai < 2; ++ai)
; #pragma unroll
;             for (int m = 0; m < 4; ++m) { const int rl = ai * HALF + wr * 64 + m * 16 + fr; const size_t off = (size_t)(u.pm * BM + rl) * ldc + col0; float q = 0.f;
; #pragma unroll
;                 for (int bj = 0; bj < 2; ++bj) { const u32x4 hb = *(const u32x4*)(xb + off + bj * HALF);
;                     const f32x4 b0 = (f32x4){__uint_as_float(hb.x << 16), __uint_as_float(hb.x & 0xffff0000u), __uint_as_float(hb.y << 16), __uint_as_float(hb.y & 0xffff0000u)};
;                     const f32x4 b1 = (f32x4){__uint_as_float(hb.z << 16), __uint_as_float(hb.z & 0xffff0000u), __uint_as_float(hb.w << 16), __uint_as_float(hb.w & 0xffff0000u)};
;                     const f32x4 v0 = b0 + acc[ai][bj][m][0], v1 = b1 + acc[ai][bj][m][1];
;                     u32x4 w; w.x = cvt_pk_bf16(v0[0], v0[1]); w.y = cvt_pk_bf16(v0[2], v0[3]); w.z = cvt_pk_bf16(v1[0], v1[1]); w.w = cvt_pk_bf16(v1[2], v1[3]);
;                     *(u32x4*)(xb + off + bj * HALF) = w;
;                     q += (v0[0] * v0[0] + v0[1] * v0[1]) + (v0[2] * v0[2] + v0[3] * v0[3]) + (v1[0] * v1[0] + v1[1] * v1[1]) + (v1[2] * v1[2] + v1[3] * v1[3]); }
;                 q += __shfl_xor(q, 16); q += __shfl_xor(q, 32);
;                 if (fq == 0) P[rl * 4 + wc] = q; }
.LBB0_217:
	s_or_b64 exec, exec, s[2:3]
	v_add_u32_e32 v56, 0x90, v148
	v_add_u32_e32 v58, s4, v56
	v_ashrrev_i32_e32 v59, 31, v58
	v_readlane_b32 s2, v252, 36
	v_lshlrev_b64 v[58:59], 12, v[58:59]
	v_readlane_b32 s3, v252, 37
	s_nop 1
	v_lshl_add_u64 v[58:59], s[2:3], 0, v[58:59]
	v_lshl_add_u64 v[62:63], v[2:3], 1, v[58:59]
	s_waitcnt vmcnt(15)
	v_lshlrev_b32_e32 v64, 16, v196
	v_and_b32_e32 v65, 0xffff0000, v196
	v_lshlrev_b32_e32 v58, 16, v197
	v_and_b32_e32 v59, 0xffff0000, v197
	v_lshlrev_b32_e32 v66, 16, v198
	v_and_b32_e32 v67, 0xffff0000, v198
	v_lshlrev_b32_e32 v60, 16, v199
	v_and_b32_e32 v61, 0xffff0000, v199
	v_pk_add_f32 v[58:59], v[54:55], v[58:59]
	v_pk_add_f32 v[64:65], v[52:53], v[64:65]
	v_pk_add_f32 v[60:61], v[50:51], v[60:61]
	v_pk_add_f32 v[66:67], v[48:49], v[66:67]
	v_cvt_pk_bf16_f32 v48, v64, v65
	v_cvt_pk_bf16_f32 v49, v58, v59
	s_waitcnt lgkmcnt(0)
	v_mul_f32_e32 v57, v65, v65
	v_cvt_pk_bf16_f32 v50, v66, v67
	v_cvt_pk_bf16_f32 v51, v60, v61
	v_mul_f32_e32 v59, v59, v59
	v_mul_f32_e32 v65, v67, v67
	v_fmac_f32_e32 v57, v64, v64
	v_fmac_f32_e32 v59, v58, v58
	v_mul_f32_e32 v61, v61, v61
	v_fmac_f32_e32 v65, v66, v66
	v_add_f32_e32 v57, v57, v59
	v_fmac_f32_e32 v61, v60, v60
	v_add_f32_e32 v57, v65, v57
	v_add_f32_e32 v57, v61, v57
	global_store_dwordx4 v[62:63], v[48:51], off
	s_waitcnt vmcnt(15)
	v_lshlrev_b32_e32 v58, 16, v200
	v_and_b32_e32 v59, 0xffff0000, v200
	v_lshlrev_b32_e32 v52, 16, v201
	v_and_b32_e32 v53, 0xffff0000, v201
	v_lshlrev_b32_e32 v60, 16, v202
	v_and_b32_e32 v61, 0xffff0000, v202
	v_lshlrev_b32_e32 v54, 16, v203
	v_and_b32_e32 v55, 0xffff0000, v203
	v_pk_add_f32 v[46:47], v[46:47], v[52:53]
	v_pk_add_f32 v[44:45], v[44:45], v[58:59]
	v_pk_add_f32 v[52:53], v[42:43], v[54:55]
	v_pk_add_f32 v[54:55], v[40:41], v[60:61]
	v_mul_f32_e32 v40, v45, v45
	v_mul_f32_e32 v41, v47, v47
	v_mul_f32_e32 v42, v55, v55
	v_fmac_f32_e32 v40, v44, v44
	v_fmac_f32_e32 v41, v46, v46
	v_mul_f32_e32 v43, v53, v53
	v_fmac_f32_e32 v42, v54, v54
	v_add_f32_e32 v40, v40, v41
	v_add_f32_e32 v40, v42, v40
	v_fmac_f32_e32 v43, v52, v52
	v_add_f32_e32 v40, v43, v40
	v_add_f32_e32 v40, v57, v40
	ds_bpermute_b32 v41, v128, v40
	v_cvt_pk_bf16_f32 v42, v44, v45
	v_cvt_pk_bf16_f32 v43, v46, v47
	v_cvt_pk_bf16_f32 v44, v54, v55
	v_cvt_pk_bf16_f32 v45, v52, v53
	s_waitcnt lgkmcnt(0)
	v_add_f32_e32 v40, v40, v41
	ds_bpermute_b32 v41, v120, v40
	global_store_dwordx4 v[62:63], v[42:45], off offset:256
	s_and_saveexec_b64 s[2:3], vcc
	s_cbranch_execz .LBB0_219
	v_lshl_add_u32 v42, v56, 4, s5
	s_waitcnt lgkmcnt(0)
	v_add_f32_e32 v40, v40, v41
	ds_write_b32 v42, v40
; __device__ __forceinline__ unsigned cvt_pk_bf16(float lo, float hi) { unsigned r; asm volatile("v_cvt_pk_bf16_f32 %0, %1, %2" : "=v"(r) : "v"(lo), "v"(hi)); return r; }
;     __device__ __forceinline__ void fused(f32x4 (&acc)[2][2][4][2], const Unit& u, int wr, int wc, int fr, int fq, PG8_LAS unsigned char* lds, int wid, int lane) const {
;     ...
;         for (int ai = 0; ai < 2; ++ai)
; #pragma unroll
;             for (int m = 0; m < 4; ++m) { const int rl = ai * HALF + wr * 64 + m * 16 + fr; const size_t off = (size_t)(u.pm * BM + rl) * ldc + col0; float q = 0.f;
; #pragma unroll
;                 for (int bj = 0; bj < 2; ++bj) { const u32x4 hb = *(const u32x4*)(xb + off + bj * HALF);
;                     const f32x4 b0 = (f32x4){__uint_as_float(hb.x << 16), __uint_as_float(hb.x & 0xffff0000u), __uint_as_float(hb.y << 16), __uint_as_float(hb.y & 0xffff0000u)};
;                     const f32x4 b1 = (f32x4){__uint_as_float(hb.z << 16), __uint_as_float(hb.z & 0xffff0000u), __uint_as_float(hb.w << 16), __uint_as_float(hb.w & 0xffff0000u)};
;                     const f32x4 v0 = b0 + acc[ai][bj][m][0], v1 = b1 + acc[ai][bj][m][1];
;                     u32x4 w; w.x = cvt_pk_bf16(v0[0], v0[1]); w.y = cvt_pk_bf16(v0[2], v0[3]); w.z = cvt_pk_bf16(v1[0], v1[1]); w.w = cvt_pk_bf16(v1[2], v1[3]);
;                     *(u32x4*)(xb + off + bj * HALF) = w;
;                     q += (v0[0] * v0[0] + v0[1] * v0[1]) + (v0[2] * v0[2] + v0[3] * v0[3]) + (v1[0] * v1[0] + v1[1] * v1[1]) + (v1[2] * v1[2] + v1[3] * v1[3]); }
;                 q += __shfl_xor(q, 16); q += __shfl_xor(q, 32);
;                 if (fq == 0) P[rl * 4 + wc] = q; }
.LBB0_219:
	s_or_b64 exec, exec, s[2:3]
	v_add_u32_e32 v40, 0xa0, v148
	v_add_u32_e32 v42, s4, v40
	v_ashrrev_i32_e32 v43, 31, v42
	v_readlane_b32 s2, v252, 36
	v_lshlrev_b64 v[42:43], 12, v[42:43]
	v_readlane_b32 s3, v252, 37
	s_nop 1
	v_lshl_add_u64 v[42:43], s[2:3], 0, v[42:43]
	v_lshl_add_u64 v[46:47], v[2:3], 1, v[42:43]
	s_waitcnt vmcnt(15)
	v_lshlrev_b32_e32 v48, 16, v204
	v_and_b32_e32 v49, 0xffff0000, v204
	v_lshlrev_b32_e32 v42, 16, v205
	v_and_b32_e32 v43, 0xffff0000, v205
	v_lshlrev_b32_e32 v50, 16, v206
	v_and_b32_e32 v51, 0xffff0000, v206
	v_lshlrev_b32_e32 v44, 16, v207
	v_and_b32_e32 v45, 0xffff0000, v207
	v_pk_add_f32 v[42:43], v[38:39], v[42:43]
	v_pk_add_f32 v[48:49], v[36:37], v[48:49]
	v_pk_add_f32 v[44:45], v[34:35], v[44:45]
	v_pk_add_f32 v[50:51], v[32:33], v[50:51]
	v_cvt_pk_bf16_f32 v32, v48, v49
	v_cvt_pk_bf16_f32 v33, v42, v43
	s_waitcnt lgkmcnt(0)
	v_mul_f32_e32 v41, v49, v49
	v_cvt_pk_bf16_f32 v34, v50, v51
	v_cvt_pk_bf16_f32 v35, v44, v45
	v_mul_f32_e32 v43, v43, v43
	v_mul_f32_e32 v49, v51, v51
	v_fmac_f32_e32 v41, v48, v48
	v_fmac_f32_e32 v43, v42, v42
	v_mul_f32_e32 v45, v45, v45
	v_fmac_f32_e32 v49, v50, v50
	v_add_f32_e32 v41, v41, v43
	v_fmac_f32_e32 v45, v44, v44
	v_add_f32_e32 v41, v49, v41
	v_add_f32_e32 v41, v45, v41
	global_store_dwordx4 v[46:47], v[32:35], off
	s_waitcnt vmcnt(15)
	v_lshlrev_b32_e32 v42, 16, v224
	v_and_b32_e32 v43, 0xffff0000, v224
	v_lshlrev_b32_e32 v36, 16, v225
	v_and_b32_e32 v37, 0xffff0000, v225
	v_lshlrev_b32_e32 v44, 16, v226
	v_and_b32_e32 v45, 0xffff0000, v226
	v_lshlrev_b32_e32 v38, 16, v227
	v_and_b32_e32 v39, 0xffff0000, v227
	v_pk_add_f32 v[30:31], v[30:31], v[36:37]
	v_pk_add_f32 v[28:29], v[28:29], v[42:43]
	v_pk_add_f32 v[36:37], v[26:27], v[38:39]
	v_pk_add_f32 v[38:39], v[24:25], v[44:45]
	v_mul_f32_e32 v24, v29, v29
	v_mul_f32_e32 v25, v31, v31
	v_mul_f32_e32 v26, v39, v39
	v_fmac_f32_e32 v24, v28, v28
	v_fmac_f32_e32 v25, v30, v30
	v_mul_f32_e32 v27, v37, v37
	v_fmac_f32_e32 v26, v38, v38
	v_add_f32_e32 v24, v24, v25
	v_add_f32_e32 v24, v26, v24
	v_fmac_f32_e32 v27, v36, v36
	v_add_f32_e32 v24, v27, v24
	v_add_f32_e32 v24, v41, v24
	ds_bpermute_b32 v25, v128, v24
	v_cvt_pk_bf16_f32 v26, v28, v29
	v_cvt_pk_bf16_f32 v27, v30, v31
	v_cvt_pk_bf16_f32 v28, v38, v39
	v_cvt_pk_bf16_f32 v29, v36, v37
	s_waitcnt lgkmcnt(0)
	v_add_f32_e32 v24, v24, v25
	ds_bpermute_b32 v25, v120, v24
	global_store_dwordx4 v[46:47], v[26:29], off offset:256
	s_and_saveexec_b64 s[2:3], vcc
	s_cbranch_execz .LBB0_221
	v_lshl_add_u32 v26, v40, 4, s5
	s_waitcnt lgkmcnt(0)
	v_add_f32_e32 v24, v24, v25
	ds_write_b32 v26, v24
.LBB0_221:
	s_or_b64 exec, exec, s[2:3]
	v_add_u32_e32 v24, 0xb0, v148
	v_add_u32_e32 v26, s4, v24
	v_ashrrev_i32_e32 v27, 31, v26
	v_readlane_b32 s2, v252, 36
	v_lshlrev_b64 v[26:27], 12, v[26:27]
	v_readlane_b32 s3, v252, 37
	s_nop 1
	v_lshl_add_u64 v[26:27], s[2:3], 0, v[26:27]
	v_lshl_add_u64 v[30:31], v[2:3], 1, v[26:27]
	s_waitcnt vmcnt(15)
	v_lshlrev_b32_e32 v2, 16, v228
	v_and_b32_e32 v3, 0xffff0000, v228
	v_lshlrev_b32_e32 v26, 16, v229
	v_and_b32_e32 v27, 0xffff0000, v229
	v_lshlrev_b32_e32 v32, 16, v230
	v_and_b32_e32 v33, 0xffff0000, v230
	v_lshlrev_b32_e32 v28, 16, v231
	v_and_b32_e32 v29, 0xffff0000, v231
	v_pk_add_f32 v[26:27], v[22:23], v[26:27]
	v_pk_add_f32 v[2:3], v[20:21], v[2:3]
	v_pk_add_f32 v[28:29], v[18:19], v[28:29]
	v_pk_add_f32 v[32:33], v[16:17], v[32:33]
	v_cvt_pk_bf16_f32 v16, v2, v3
	v_cvt_pk_bf16_f32 v17, v26, v27
	v_mul_f32_e32 v3, v3, v3
	v_cvt_pk_bf16_f32 v18, v32, v33
	v_cvt_pk_bf16_f32 v19, v28, v29
	s_waitcnt lgkmcnt(0)
	v_mul_f32_e32 v25, v27, v27
	v_mul_f32_e32 v27, v33, v33
	v_fmac_f32_e32 v3, v2, v2
	v_fmac_f32_e32 v25, v26, v26
	v_mul_f32_e32 v29, v29, v29
	v_fmac_f32_e32 v27, v32, v32
	v_add_f32_e32 v2, v3, v25
	v_fmac_f32_e32 v29, v28, v28
	v_add_f32_e32 v2, v27, v2
	v_add_f32_e32 v25, v29, v2
	global_store_dwordx4 v[30:31], v[16:19], off
	s_waitcnt vmcnt(15)
	v_lshlrev_b32_e32 v2, 16, v232
	v_and_b32_e32 v3, 0xffff0000, v232
	v_lshlrev_b32_e32 v20, 16, v233
	v_and_b32_e32 v21, 0xffff0000, v233
	v_lshlrev_b32_e32 v26, 16, v234
	v_and_b32_e32 v27, 0xffff0000, v234
	v_lshlrev_b32_e32 v22, 16, v235
	v_and_b32_e32 v23, 0xffff0000, v235
	v_pk_add_f32 v[14:15], v[14:15], v[20:21]
	v_pk_add_f32 v[2:3], v[12:13], v[2:3]
	v_pk_add_f32 v[12:13], v[10:11], v[22:23]
	v_pk_add_f32 v[10:11], v[8:9], v[26:27]
	v_mul_f32_e32 v8, v3, v3
	v_mul_f32_e32 v9, v15, v15
	v_mul_f32_e32 v20, v11, v11
	v_fmac_f32_e32 v8, v2, v2
	v_fmac_f32_e32 v9, v14, v14
	v_mul_f32_e32 v21, v13, v13
	v_fmac_f32_e32 v20, v10, v10
	v_add_f32_e32 v8, v8, v9
	v_add_f32_e32 v8, v20, v8
	v_fmac_f32_e32 v21, v12, v12
	v_add_f32_e32 v8, v21, v8
	v_add_f32_e32 v9, v25, v8
	ds_bpermute_b32 v20, v128, v9
	v_cvt_pk_bf16_f32 v8, v2, v3
	s_waitcnt lgkmcnt(0)
	v_add_f32_e32 v2, v9, v20
	ds_bpermute_b32 v3, v120, v2
	v_cvt_pk_bf16_f32 v9, v14, v15
	v_cvt_pk_bf16_f32 v10, v10, v11
	v_cvt_pk_bf16_f32 v11, v12, v13
	global_store_dwordx4 v[30:31], v[8:11], off offset:256
	s_and_saveexec_b64 s[2:3], vcc
	s_cbranch_execz .LBB0_223
	v_lshl_add_u32 v8, v24, 4, s5
	s_waitcnt lgkmcnt(0)
	v_add_f32_e32 v2, v2, v3
	ds_write_b32 v8, v2

; #define PG8_LAS __attribute__((address_space(3)))
;     __device__ __forceinline__ void khook(f32x4 (&acc)[2][2][4][2], int hb, int wr, int fr, PG8_LAS unsigned char* lds) const {
;         const PG8_LAS float* RT = (const PG8_LAS float*)(lds + 131072 + 11264) + hb * 256 + wr * 64 + fr;
; #pragma unroll
;         for (int ai = 0; ai < 2; ++ai)
; #pragma unroll
;             for (int m = 0; m < 4; ++m) { const float r = RT[ai * HALF + m * 16];
; #pragma unroll
;                 for (int bj = 0; bj < 2; ++bj)
; #pragma unroll
;                     for (int n = 0; n < 2; ++n) acc[ai][bj][m][n] = acc[ai][bj][m][n] * r; } }
;     __device__ __forceinline__ void fused(f32x4 (&acc)[2][2][4][2], const Unit& u, int wr, int wc, int fr, int fq, PG8_LAS unsigned char* lds, int wid, int lane) const {
;         khook(acc, 0, wr, fr, lds);
;         PG8_LAS float* P = (PG8_LAS float*)lds;
;         const int col0 = u.pn * BM + wc * 32 + 8 * fq;
; #pragma unroll
;         for (int ai = 0; ai < 2; ++ai)
; #pragma unroll
;             for (int m = 0; m < 4; ++m) { const int rl = ai * HALF + wr * 64 + m * 16 + fr; const size_t off = (size_t)(u.pm * BM + rl) * ldc + col0; float q = 0.f;
; #pragma unroll
;                 for (int bj = 0; bj < 2; ++bj) { const u32x4 hb = *(const u32x4*)(xb + off + bj * HALF);
;                     const f32x4 b0 = (f32x4){__uint_as_float(hb.x << 16), __uint_as_float(hb.x & 0xffff0000u), __uint_as_float(hb.y << 16), __uint_as_float(hb.y & 0xffff0000u)};
;                     const f32x4 b1 = (f32x4){__uint_as_float(hb.z << 16), __uint_as_float(hb.z & 0xffff0000u), __uint_as_float(hb.w << 16), __uint_as_float(hb.w & 0xffff0000u)};
;                     const f32x4 v0 = b0 + acc[ai][bj][m][0], v1 = b1 + acc[ai][bj][m][1];
;                     u32x4 w; w.x = cvt_pk_bf16(v0[0], v0[1]); w.y = cvt_pk_bf16(v0[2], v0[3]); w.z = cvt_pk_bf16(v1[0], v1[1]); w.w = cvt_pk_bf16(v1[2], v1[3]);
;                     *(u32x4*)(xb + off + bj * HALF) = w;
;                     q += (v0[0] * v0[0] + v0[1] * v0[1]) + (v0[2] * v0[2] + v0[3] * v0[3]) + (v1[0] * v1[0] + v1[1] * v1[1]) + (v1[2] * v1[2] + v1[3] * v1[3]); }
;                 q += __shfl_xor(q, 16); q += __shfl_xor(q, 32);
;                 if (fq == 0) P[rl * 4 + wc] = q; }
.LBB0_254:
	s_lshl_b32 s2, s45, 5
	s_lshl_b32 s3, s0, 8
	s_or_b32 s2, s3, s2
	s_lshl_b32 s3, s44, 8
	v_lshrrev_b32_e32 v208, 1, v145
	v_and_or_b32 v208, v208, 24, s2
	v_add_u32_e32 v209, s3, v144
	v_lshlrev_b32_e32 v209, 12, v209
	v_lshl_add_u32 v209, v208, 1, v209
	v_readlane_b32 s2, v252, 36
	v_readlane_b32 s3, v252, 37
	s_nop 4
	global_load_dwordx4 v[158:161], v209, s[2:3]
	global_load_dwordx4 v[162:165], v209, s[2:3] offset:256
	v_add_u32_e32 v209, 0x10000, v209
	global_load_dwordx4 v[166:169], v209, s[2:3]
	global_load_dwordx4 v[170:173], v209, s[2:3] offset:256
	v_add_u32_e32 v209, 0x10000, v209
	global_load_dwordx4 v[174:177], v209, s[2:3]
	global_load_dwordx4 v[178:181], v209, s[2:3] offset:256
	v_add_u32_e32 v209, 0x10000, v209
	global_load_dwordx4 v[184:187], v209, s[2:3]
	global_load_dwordx4 v[188:191], v209, s[2:3] offset:256
	v_add_u32_e32 v209, 0x50000, v209
	global_load_dwordx4 v[192:195], v209, s[2:3]
	global_load_dwordx4 v[196:199], v209, s[2:3] offset:256
	v_add_u32_e32 v209, 0x10000, v209
	global_load_dwordx4 v[200:203], v209, s[2:3]
	global_load_dwordx4 v[204:207], v209, s[2:3] offset:256
	v_add_u32_e32 v209, 0x10000, v209
	global_load_dwordx4 v[224:227], v209, s[2:3]
	global_load_dwordx4 v[228:231], v209, s[2:3] offset:256
	v_add_u32_e32 v209, 0x10000, v209
	global_load_dwordx4 v[232:235], v209, s[2:3]
	global_load_dwordx4 v[236:239], v209, s[2:3] offset:256
	s_waitcnt vmcnt(16)
	s_cmpk_gt_u32 s1, 0xff
	s_cbranch_scc1 .LBB0_256
	s_barrier
.LBB0_256:
	s_lshl_b32 s2, s45, 5
	s_lshl_b32 s3, s0, 8
	s_lshl_b32 s4, s44, 8
	v_lshrrev_b32_e32 v0, 1, v145
	s_or_b32 s2, s3, s2
	v_add_u32_e32 v136, s4, v144
	v_and_or_b32 v2, v0, 24, s2
	v_ashrrev_i32_e32 v137, 31, v136
	v_readlane_b32 s2, v252, 36
	v_lshlrev_b64 v[136:137], 12, v[136:137]
	v_readlane_b32 s3, v252, 37
	v_ashrrev_i32_e32 v3, 31, v2
	s_barrier
	v_lshl_add_u64 v[136:137], s[2:3], 0, v[136:137]
	v_lshl_add_u64 v[152:153], v[2:3], 1, v[136:137]
	v_lshl_add_u32 v0, v146, 2, s73
	v_add_u32_e32 v0, 0x22c00, v0
	ds_read2_b32 v[142:143], v0 offset1:16
	ds_read2_b32 v[140:141], v0 offset0:32 offset1:48
	ds_read2_b32 v[138:139], v0 offset0:128 offset1:144
	ds_read2_b32 v[136:137], v0 offset0:160 offset1:176
	v_and_b32_e32 v0, 63, v145
	v_cmp_lt_i32_e32 vcc, v219, v214
	s_lshl_b32 s2, s45, 2
	s_add_i32 s5, s2, 0
	s_waitcnt vmcnt(15)
	v_lshlrev_b32_e32 v146, 16, v158
	v_and_b32_e32 v147, 0xffff0000, v158
	v_lshlrev_b32_e32 v148, 16, v159
	v_and_b32_e32 v149, 0xffff0000, v159
	v_lshlrev_b32_e32 v154, 16, v160
	v_and_b32_e32 v155, 0xffff0000, v160
	v_lshlrev_b32_e32 v150, 16, v161
	v_and_b32_e32 v151, 0xffff0000, v161
	s_waitcnt lgkmcnt(0)
	v_pk_fma_f32 v[134:135], v[134:135], v[142:143], v[148:149] op_sel_hi:[1,0,1]
	v_pk_fma_f32 v[156:157], v[132:133], v[142:143], v[146:147] op_sel_hi:[1,0,1]
	v_pk_fma_f32 v[150:151], v[130:131], v[142:143], v[150:151] op_sel_hi:[1,0,1]
	v_pk_fma_f32 v[154:155], v[128:129], v[142:143], v[154:155] op_sel_hi:[1,0,1]
	v_cvt_pk_bf16_f32 v130, v156, v157
	v_cvt_pk_bf16_f32 v131, v134, v135
	v_mul_f32_e32 v145, v157, v157
	v_cvt_pk_bf16_f32 v132, v154, v155
	v_cvt_pk_bf16_f32 v133, v150, v151
	v_mul_f32_e32 v135, v135, v135
	v_mul_f32_e32 v155, v155, v155
	v_fmac_f32_e32 v145, v156, v156
	v_fmac_f32_e32 v135, v134, v134
	v_mul_f32_e32 v151, v151, v151
	v_fmac_f32_e32 v155, v154, v154
	v_add_f32_e32 v134, v145, v135
	v_fmac_f32_e32 v151, v150, v150
	v_add_f32_e32 v134, v155, v134
	v_add_f32_e32 v145, v151, v134
	v_cndmask_b32_e32 v128, v213, v219, vcc
	v_lshlrev_b32_e32 v128, 2, v128
	v_cmp_lt_i32_e32 vcc, v220, v214
	global_store_dwordx4 v[152:153], v[130:133], off
	s_waitcnt vmcnt(15)
	v_lshlrev_b32_e32 v134, 16, v162
	v_and_b32_e32 v135, 0xffff0000, v162
	v_lshlrev_b32_e32 v146, 16, v163
	v_and_b32_e32 v147, 0xffff0000, v163
	v_lshlrev_b32_e32 v150, 16, v164
	v_and_b32_e32 v151, 0xffff0000, v164
	v_pk_fma_f32 v[126:127], v[126:127], v[142:143], v[146:147] op_sel_hi:[1,0,1]
	v_pk_fma_f32 v[124:125], v[124:125], v[142:143], v[134:135] op_sel_hi:[1,0,1]
	v_lshlrev_b32_e32 v148, 16, v165
	v_and_b32_e32 v149, 0xffff0000, v165
	v_pk_fma_f32 v[146:147], v[120:121], v[142:143], v[150:151] op_sel_hi:[1,0,1]
	v_mul_f32_e32 v120, v125, v125
	v_mul_f32_e32 v121, v127, v127
	v_pk_fma_f32 v[134:135], v[122:123], v[142:143], v[148:149] op_sel_hi:[1,0,1]
	v_mul_f32_e32 v122, v147, v147
	v_fmac_f32_e32 v120, v124, v124
	v_fmac_f32_e32 v121, v126, v126
	v_mul_f32_e32 v123, v135, v135
	v_fmac_f32_e32 v122, v146, v146
	v_add_f32_e32 v120, v120, v121
	v_fmac_f32_e32 v123, v134, v134
	v_add_f32_e32 v120, v122, v120
	v_add_f32_e32 v120, v123, v120
	v_add_f32_e32 v120, v145, v120
	ds_bpermute_b32 v121, v128, v120
	v_cndmask_b32_e32 v129, v213, v220, vcc
	v_cmp_gt_u32_e32 vcc, 16, v0
	v_cvt_pk_bf16_f32 v124, v124, v125
	v_cvt_pk_bf16_f32 v125, v126, v127
	s_waitcnt lgkmcnt(0)
	v_add_f32_e32 v121, v120, v121
	v_lshlrev_b32_e32 v120, 2, v129
	ds_bpermute_b32 v122, v120, v121
	v_cvt_pk_bf16_f32 v126, v146, v147
	v_cvt_pk_bf16_f32 v127, v134, v135
	global_store_dwordx4 v[152:153], v[124:127], off offset:256
	s_and_saveexec_b64 s[2:3], vcc
	s_cbranch_execz .LBB0_258
	v_lshl_add_u32 v123, v144, 4, s5
	s_waitcnt lgkmcnt(0)
	v_add_f32_e32 v121, v121, v122
	ds_write_b32 v123, v121
; #define PG8_LAS __attribute__((address_space(3)))
; __device__ __forceinline__ unsigned cvt_pk_bf16(float lo, float hi) { unsigned r; asm volatile("v_cvt_pk_bf16_f32 %0, %1, %2" : "=v"(r) : "v"(lo), "v"(hi)); return r; }
;     __device__ __forceinline__ void khook(f32x4 (&acc)[2][2][4][2], int hb, int wr, int fr, PG8_LAS unsigned char* lds) const {
;     ...
;             for (int m = 0; m < 4; ++m) { const float r = RT[ai * HALF + m * 16];
; #pragma unroll
;                 for (int bj = 0; bj < 2; ++bj)
; #pragma unroll
;                     for (int n = 0; n < 2; ++n) acc[ai][bj][m][n] = acc[ai][bj][m][n] * r; } }
;     __device__ __forceinline__ void fused(f32x4 (&acc)[2][2][4][2], const Unit& u, int wr, int wc, int fr, int fq, PG8_LAS unsigned char* lds, int wid, int lane) const {
;         khook(acc, 0, wr, fr, lds);
;         PG8_LAS float* P = (PG8_LAS float*)lds;
;         const int col0 = u.pn * BM + wc * 32 + 8 * fq;
; #pragma unroll
;         for (int ai = 0; ai < 2; ++ai)
; #pragma unroll
;             for (int m = 0; m < 4; ++m) { const int rl = ai * HALF + wr * 64 + m * 16 + fr; const size_t off = (size_t)(u.pm * BM + rl) * ldc + col0; float q = 0.f;
; #pragma unroll
;                 for (int bj = 0; bj < 2; ++bj) { const u32x4 hb = *(const u32x4*)(xb + off + bj * HALF);
;                     const f32x4 b0 = (f32x4){__uint_as_float(hb.x << 16), __uint_as_float(hb.x & 0xffff0000u), __uint_as_float(hb.y << 16), __uint_as_float(hb.y & 0xffff0000u)};
;                     const f32x4 b1 = (f32x4){__uint_as_float(hb.z << 16), __uint_as_float(hb.z & 0xffff0000u), __uint_as_float(hb.w << 16), __uint_as_float(hb.w & 0xffff0000u)};
;                     const f32x4 v0 = b0 + acc[ai][bj][m][0], v1 = b1 + acc[ai][bj][m][1];
;                     u32x4 w; w.x = cvt_pk_bf16(v0[0], v0[1]); w.y = cvt_pk_bf16(v0[2], v0[3]); w.z = cvt_pk_bf16(v1[0], v1[1]); w.w = cvt_pk_bf16(v1[2], v1[3]);
;                     *(u32x4*)(xb + off + bj * HALF) = w;
;                     q += (v0[0] * v0[0] + v0[1] * v0[1]) + (v0[2] * v0[2] + v0[3] * v0[3]) + (v1[0] * v1[0] + v1[1] * v1[1]) + (v1[2] * v1[2] + v1[3] * v1[3]); }
;                 q += __shfl_xor(q, 16); q += __shfl_xor(q, 32);
;                 if (fq == 0) P[rl * 4 + wc] = q; }
.LBB0_258:
	s_or_b64 exec, exec, s[2:3]
	v_or_b32_e32 v121, 16, v144
	s_waitcnt lgkmcnt(0)
	v_add_u32_e32 v122, s4, v121
	v_ashrrev_i32_e32 v123, 31, v122
	v_readlane_b32 s2, v252, 36
	v_lshlrev_b64 v[122:123], 12, v[122:123]
	v_readlane_b32 s3, v252, 37
	v_mov_b32_e32 v130, v143
	s_nop 0
	v_lshl_add_u64 v[122:123], s[2:3], 0, v[122:123]
	v_lshl_add_u64 v[126:127], v[2:3], 1, v[122:123]
	s_waitcnt vmcnt(15)
	v_lshlrev_b32_e32 v132, 16, v166
	v_and_b32_e32 v133, 0xffff0000, v166
	v_lshlrev_b32_e32 v122, 16, v167
	v_and_b32_e32 v123, 0xffff0000, v167
	v_lshlrev_b32_e32 v134, 16, v168
	v_and_b32_e32 v135, 0xffff0000, v168
	v_lshlrev_b32_e32 v124, 16, v169
	v_and_b32_e32 v125, 0xffff0000, v169
	v_pk_fma_f32 v[122:123], v[118:119], v[130:131], v[122:123] op_sel_hi:[1,0,1]
	v_pk_fma_f32 v[132:133], v[116:117], v[130:131], v[132:133] op_sel_hi:[1,0,1]
	v_pk_fma_f32 v[124:125], v[114:115], v[130:131], v[124:125] op_sel_hi:[1,0,1]
	v_pk_fma_f32 v[134:135], v[112:113], v[130:131], v[134:135] op_sel_hi:[1,0,1]
	v_cvt_pk_bf16_f32 v112, v132, v133
	v_cvt_pk_bf16_f32 v113, v122, v123
	v_mul_f32_e32 v129, v133, v133
	v_cvt_pk_bf16_f32 v114, v134, v135
	v_cvt_pk_bf16_f32 v115, v124, v125
	v_mul_f32_e32 v123, v123, v123
	v_mul_f32_e32 v131, v135, v135
	v_fmac_f32_e32 v129, v132, v132
	v_fmac_f32_e32 v123, v122, v122
	v_mul_f32_e32 v125, v125, v125
	v_fmac_f32_e32 v131, v134, v134
	v_add_f32_e32 v122, v129, v123
	v_fmac_f32_e32 v125, v124, v124
	v_add_f32_e32 v122, v131, v122
	v_add_f32_e32 v129, v125, v122
	global_store_dwordx4 v[126:127], v[112:115], off
	s_waitcnt vmcnt(15)
	v_lshlrev_b32_e32 v122, 16, v170
	v_and_b32_e32 v123, 0xffff0000, v170
	v_lshlrev_b32_e32 v116, 16, v171
	v_and_b32_e32 v117, 0xffff0000, v171
	v_lshlrev_b32_e32 v124, 16, v172
	v_and_b32_e32 v125, 0xffff0000, v172
	v_lshlrev_b32_e32 v118, 16, v173
	v_and_b32_e32 v119, 0xffff0000, v173
	v_pk_fma_f32 v[110:111], v[110:111], v[130:131], v[116:117] op_sel_hi:[1,0,1]
	v_pk_fma_f32 v[108:109], v[108:109], v[130:131], v[122:123] op_sel_hi:[1,0,1]
	v_pk_fma_f32 v[116:117], v[106:107], v[130:131], v[118:119] op_sel_hi:[1,0,1]
	v_pk_fma_f32 v[118:119], v[104:105], v[130:131], v[124:125] op_sel_hi:[1,0,1]
	v_mul_f32_e32 v104, v109, v109
	v_mul_f32_e32 v105, v111, v111
	v_mul_f32_e32 v106, v119, v119
	v_fmac_f32_e32 v104, v108, v108
	v_fmac_f32_e32 v105, v110, v110
	v_mul_f32_e32 v107, v117, v117
	v_fmac_f32_e32 v106, v118, v118
	v_add_f32_e32 v104, v104, v105
	v_add_f32_e32 v104, v106, v104
	v_fmac_f32_e32 v107, v116, v116
	v_add_f32_e32 v104, v107, v104
	v_add_f32_e32 v104, v129, v104
	ds_bpermute_b32 v105, v128, v104
	v_cvt_pk_bf16_f32 v106, v108, v109
	v_cvt_pk_bf16_f32 v107, v110, v111
	v_cvt_pk_bf16_f32 v108, v118, v119
	v_cvt_pk_bf16_f32 v109, v116, v117
	s_waitcnt lgkmcnt(0)
	v_add_f32_e32 v104, v104, v105
	ds_bpermute_b32 v105, v120, v104
	global_store_dwordx4 v[126:127], v[106:109], off offset:256
	s_and_saveexec_b64 s[2:3], vcc
	s_cbranch_execz .LBB0_260
	v_lshl_add_u32 v106, v121, 4, s5
	s_waitcnt lgkmcnt(0)
	v_add_f32_e32 v104, v104, v105
	ds_write_b32 v106, v104
.LBB0_260:
	s_or_b64 exec, exec, s[2:3]
	v_or_b32_e32 v104, 32, v144
	v_add_u32_e32 v106, s4, v104
	v_ashrrev_i32_e32 v107, 31, v106
	v_readlane_b32 s2, v252, 36
	v_lshlrev_b64 v[106:107], 12, v[106:107]
	v_readlane_b32 s3, v252, 37
	s_nop 1
	v_lshl_add_u64 v[106:107], s[2:3], 0, v[106:107]
	v_lshl_add_u64 v[110:111], v[2:3], 1, v[106:107]
	s_waitcnt vmcnt(15)
	v_lshlrev_b32_e32 v112, 16, v174
	v_and_b32_e32 v113, 0xffff0000, v174
	v_lshlrev_b32_e32 v106, 16, v175
	v_and_b32_e32 v107, 0xffff0000, v175
	v_lshlrev_b32_e32 v114, 16, v176
	v_and_b32_e32 v115, 0xffff0000, v176
	v_lshlrev_b32_e32 v108, 16, v177
	v_and_b32_e32 v109, 0xffff0000, v177
	v_pk_fma_f32 v[106:107], v[102:103], v[140:141], v[106:107] op_sel_hi:[1,0,1]
	v_pk_fma_f32 v[112:113], v[100:101], v[140:141], v[112:113] op_sel_hi:[1,0,1]
	v_pk_fma_f32 v[108:109], v[98:99], v[140:141], v[108:109] op_sel_hi:[1,0,1]
	v_pk_fma_f32 v[114:115], v[96:97], v[140:141], v[114:115] op_sel_hi:[1,0,1]
	v_cvt_pk_bf16_f32 v96, v112, v113
	v_cvt_pk_bf16_f32 v97, v106, v107
	s_waitcnt lgkmcnt(0)
	v_mul_f32_e32 v105, v113, v113
	v_cvt_pk_bf16_f32 v98, v114, v115
	v_cvt_pk_bf16_f32 v99, v108, v109
	v_mul_f32_e32 v107, v107, v107
	v_mul_f32_e32 v113, v115, v115
	v_fmac_f32_e32 v105, v112, v112
	v_fmac_f32_e32 v107, v106, v106
	v_mul_f32_e32 v109, v109, v109
	v_fmac_f32_e32 v113, v114, v114
	v_add_f32_e32 v105, v105, v107
	v_fmac_f32_e32 v109, v108, v108
	v_add_f32_e32 v105, v113, v105
	v_add_f32_e32 v105, v109, v105
	global_store_dwordx4 v[110:111], v[96:99], off
	s_waitcnt vmcnt(15)
	v_lshlrev_b32_e32 v106, 16, v178
	v_and_b32_e32 v107, 0xffff0000, v178
	v_lshlrev_b32_e32 v100, 16, v179
	v_and_b32_e32 v101, 0xffff0000, v179
	v_lshlrev_b32_e32 v108, 16, v180
	v_and_b32_e32 v109, 0xffff0000, v180
	v_lshlrev_b32_e32 v102, 16, v181
	v_and_b32_e32 v103, 0xffff0000, v181
	v_pk_fma_f32 v[94:95], v[94:95], v[140:141], v[100:101] op_sel_hi:[1,0,1]
	v_pk_fma_f32 v[92:93], v[92:93], v[140:141], v[106:107] op_sel_hi:[1,0,1]
	v_pk_fma_f32 v[100:101], v[90:91], v[140:141], v[102:103] op_sel_hi:[1,0,1]
	v_pk_fma_f32 v[102:103], v[88:89], v[140:141], v[108:109] op_sel_hi:[1,0,1]
	v_mul_f32_e32 v88, v93, v93
	v_mul_f32_e32 v89, v95, v95
	v_mul_f32_e32 v90, v103, v103
	v_fmac_f32_e32 v88, v92, v92
	v_fmac_f32_e32 v89, v94, v94
	v_mul_f32_e32 v91, v101, v101
	v_fmac_f32_e32 v90, v102, v102
	v_add_f32_e32 v88, v88, v89
	v_add_f32_e32 v88, v90, v88
	v_fmac_f32_e32 v91, v100, v100
	v_add_f32_e32 v88, v91, v88
	v_add_f32_e32 v88, v105, v88
	ds_bpermute_b32 v89, v128, v88
	v_cvt_pk_bf16_f32 v90, v92, v93
	v_cvt_pk_bf16_f32 v91, v94, v95
	v_cvt_pk_bf16_f32 v92, v102, v103
	v_cvt_pk_bf16_f32 v93, v100, v101
	s_waitcnt lgkmcnt(0)
	v_add_f32_e32 v88, v88, v89
	ds_bpermute_b32 v89, v120, v88
	global_store_dwordx4 v[110:111], v[90:93], off offset:256
	s_and_saveexec_b64 s[2:3], vcc
	s_cbranch_execz .LBB0_262
	v_lshl_add_u32 v90, v104, 4, s5
	s_waitcnt lgkmcnt(0)
	v_add_f32_e32 v88, v88, v89
	ds_write_b32 v90, v88
; #define PG8_LAS __attribute__((address_space(3)))
; __device__ __forceinline__ unsigned cvt_pk_bf16(float lo, float hi) { unsigned r; asm volatile("v_cvt_pk_bf16_f32 %0, %1, %2" : "=v"(r) : "v"(lo), "v"(hi)); return r; }
;     __device__ __forceinline__ void khook(f32x4 (&acc)[2][2][4][2], int hb, int wr, int fr, PG8_LAS unsigned char* lds) const {
;     ...
;             for (int m = 0; m < 4; ++m) { const float r = RT[ai * HALF + m * 16];
; #pragma unroll
;                 for (int bj = 0; bj < 2; ++bj)
; #pragma unroll
;                     for (int n = 0; n < 2; ++n) acc[ai][bj][m][n] = acc[ai][bj][m][n] * r; } }
;     __device__ __forceinline__ void fused(f32x4 (&acc)[2][2][4][2], const Unit& u, int wr, int wc, int fr, int fq, PG8_LAS unsigned char* lds, int wid, int lane) const {
;         khook(acc, 0, wr, fr, lds);
;         PG8_LAS float* P = (PG8_LAS float*)lds;
;         const int col0 = u.pn * BM + wc * 32 + 8 * fq;
; #pragma unroll
;         for (int ai = 0; ai < 2; ++ai)
; #pragma unroll
;             for (int m = 0; m < 4; ++m) { const int rl = ai * HALF + wr * 64 + m * 16 + fr; const size_t off = (size_t)(u.pm * BM + rl) * ldc + col0; float q = 0.f;
; #pragma unroll
;                 for (int bj = 0; bj < 2; ++bj) { const u32x4 hb = *(const u32x4*)(xb + off + bj * HALF);
;                     const f32x4 b0 = (f32x4){__uint_as_float(hb.x << 16), __uint_as_float(hb.x & 0xffff0000u), __uint_as_float(hb.y << 16), __uint_as_float(hb.y & 0xffff0000u)};
;                     const f32x4 b1 = (f32x4){__uint_as_float(hb.z << 16), __uint_as_float(hb.z & 0xffff0000u), __uint_as_float(hb.w << 16), __uint_as_float(hb.w & 0xffff0000u)};
;                     const f32x4 v0 = b0 + acc[ai][bj][m][0], v1 = b1 + acc[ai][bj][m][1];
;                     u32x4 w; w.x = cvt_pk_bf16(v0[0], v0[1]); w.y = cvt_pk_bf16(v0[2], v0[3]); w.z = cvt_pk_bf16(v1[0], v1[1]); w.w = cvt_pk_bf16(v1[2], v1[3]);
;                     *(u32x4*)(xb + off + bj * HALF) = w;
;                     q += (v0[0] * v0[0] + v0[1] * v0[1]) + (v0[2] * v0[2] + v0[3] * v0[3]) + (v1[0] * v1[0] + v1[1] * v1[1]) + (v1[2] * v1[2] + v1[3] * v1[3]); }
;                 q += __shfl_xor(q, 16); q += __shfl_xor(q, 32);
;                 if (fq == 0) P[rl * 4 + wc] = q; }
.LBB0_262:
	s_or_b64 exec, exec, s[2:3]
	v_or_b32_e32 v88, 48, v144
	v_add_u32_e32 v90, s4, v88
	v_ashrrev_i32_e32 v91, 31, v90
	v_readlane_b32 s2, v252, 36
	v_lshlrev_b64 v[90:91], 12, v[90:91]
	v_readlane_b32 s3, v252, 37
	v_mov_b32_e32 v96, v141
	s_nop 0
	v_lshl_add_u64 v[90:91], s[2:3], 0, v[90:91]
	v_lshl_add_u64 v[94:95], v[2:3], 1, v[90:91]
	s_waitcnt vmcnt(15)
	v_lshlrev_b32_e32 v98, 16, v184
	v_and_b32_e32 v99, 0xffff0000, v184
	v_lshlrev_b32_e32 v90, 16, v185
	v_and_b32_e32 v91, 0xffff0000, v185
	v_lshlrev_b32_e32 v100, 16, v186
	v_and_b32_e32 v101, 0xffff0000, v186
	v_lshlrev_b32_e32 v92, 16, v187
	v_and_b32_e32 v93, 0xffff0000, v187
	v_pk_fma_f32 v[90:91], v[86:87], v[96:97], v[90:91] op_sel_hi:[1,0,1]
	v_pk_fma_f32 v[98:99], v[84:85], v[96:97], v[98:99] op_sel_hi:[1,0,1]
	v_pk_fma_f32 v[92:93], v[82:83], v[96:97], v[92:93] op_sel_hi:[1,0,1]
	v_pk_fma_f32 v[100:101], v[80:81], v[96:97], v[100:101] op_sel_hi:[1,0,1]
	v_cvt_pk_bf16_f32 v80, v98, v99
	v_cvt_pk_bf16_f32 v81, v90, v91
	s_waitcnt lgkmcnt(0)
	v_mul_f32_e32 v89, v99, v99
	v_cvt_pk_bf16_f32 v82, v100, v101
	v_cvt_pk_bf16_f32 v83, v92, v93
	v_mul_f32_e32 v91, v91, v91
	v_mul_f32_e32 v97, v101, v101
	v_fmac_f32_e32 v89, v98, v98
	v_fmac_f32_e32 v91, v90, v90
	v_mul_f32_e32 v93, v93, v93
	v_fmac_f32_e32 v97, v100, v100
	v_add_f32_e32 v89, v89, v91
	v_fmac_f32_e32 v93, v92, v92
	v_add_f32_e32 v89, v97, v89
	v_add_f32_e32 v89, v93, v89
	global_store_dwordx4 v[94:95], v[80:83], off
	s_waitcnt vmcnt(15)
	v_lshlrev_b32_e32 v90, 16, v188
	v_and_b32_e32 v91, 0xffff0000, v188
	v_lshlrev_b32_e32 v84, 16, v189
	v_and_b32_e32 v85, 0xffff0000, v189
	v_lshlrev_b32_e32 v92, 16, v190
	v_and_b32_e32 v93, 0xffff0000, v190
	v_lshlrev_b32_e32 v86, 16, v191
	v_and_b32_e32 v87, 0xffff0000, v191
	v_pk_fma_f32 v[78:79], v[78:79], v[96:97], v[84:85] op_sel_hi:[1,0,1]
	v_pk_fma_f32 v[76:77], v[76:77], v[96:97], v[90:91] op_sel_hi:[1,0,1]
	v_pk_fma_f32 v[84:85], v[74:75], v[96:97], v[86:87] op_sel_hi:[1,0,1]
	v_pk_fma_f32 v[86:87], v[72:73], v[96:97], v[92:93] op_sel_hi:[1,0,1]
	v_mul_f32_e32 v72, v77, v77
	v_mul_f32_e32 v73, v79, v79
	v_mul_f32_e32 v74, v87, v87
	v_fmac_f32_e32 v72, v76, v76
	v_fmac_f32_e32 v73, v78, v78
	v_mul_f32_e32 v75, v85, v85
	v_fmac_f32_e32 v74, v86, v86
	v_add_f32_e32 v72, v72, v73
	v_add_f32_e32 v72, v74, v72
	v_fmac_f32_e32 v75, v84, v84
	v_add_f32_e32 v72, v75, v72
	v_add_f32_e32 v72, v89, v72
	ds_bpermute_b32 v73, v128, v72
	v_cvt_pk_bf16_f32 v74, v76, v77
	v_cvt_pk_bf16_f32 v75, v78, v79
	v_cvt_pk_bf16_f32 v76, v86, v87
	v_cvt_pk_bf16_f32 v77, v84, v85
	s_waitcnt lgkmcnt(0)
	v_add_f32_e32 v72, v72, v73
	ds_bpermute_b32 v73, v120, v72
	global_store_dwordx4 v[94:95], v[74:77], off offset:256
	s_and_saveexec_b64 s[2:3], vcc
	s_cbranch_execz .LBB0_264
	v_lshl_add_u32 v74, v88, 4, s5
	s_waitcnt lgkmcnt(0)
	v_add_f32_e32 v72, v72, v73
	ds_write_b32 v74, v72
.LBB0_264:
	s_or_b64 exec, exec, s[2:3]
	v_add_u32_e32 v72, 0x80, v144
	v_add_u32_e32 v74, s4, v72
	v_ashrrev_i32_e32 v75, 31, v74
	v_readlane_b32 s2, v252, 36
	v_lshlrev_b64 v[74:75], 12, v[74:75]
	v_readlane_b32 s3, v252, 37
	s_nop 1
	v_lshl_add_u64 v[74:75], s[2:3], 0, v[74:75]
	v_lshl_add_u64 v[78:79], v[2:3], 1, v[74:75]
	s_waitcnt vmcnt(15)
	v_lshlrev_b32_e32 v80, 16, v192
	v_and_b32_e32 v81, 0xffff0000, v192
	v_lshlrev_b32_e32 v74, 16, v193
	v_and_b32_e32 v75, 0xffff0000, v193
	v_lshlrev_b32_e32 v82, 16, v194
	v_and_b32_e32 v83, 0xffff0000, v194
	v_lshlrev_b32_e32 v76, 16, v195
	v_and_b32_e32 v77, 0xffff0000, v195
	v_pk_fma_f32 v[74:75], v[70:71], v[138:139], v[74:75] op_sel_hi:[1,0,1]
	v_pk_fma_f32 v[80:81], v[68:69], v[138:139], v[80:81] op_sel_hi:[1,0,1]
	v_pk_fma_f32 v[76:77], v[66:67], v[138:139], v[76:77] op_sel_hi:[1,0,1]
	v_pk_fma_f32 v[82:83], v[64:65], v[138:139], v[82:83] op_sel_hi:[1,0,1]
	v_cvt_pk_bf16_f32 v64, v80, v81
	v_cvt_pk_bf16_f32 v65, v74, v75
	s_waitcnt lgkmcnt(0)
	v_mul_f32_e32 v73, v81, v81
	v_cvt_pk_bf16_f32 v66, v82, v83
	v_cvt_pk_bf16_f32 v67, v76, v77
	v_mul_f32_e32 v75, v75, v75
	v_mul_f32_e32 v81, v83, v83
	v_fmac_f32_e32 v73, v80, v80
	v_fmac_f32_e32 v75, v74, v74
	v_mul_f32_e32 v77, v77, v77
	v_fmac_f32_e32 v81, v82, v82
	v_add_f32_e32 v73, v73, v75
	v_fmac_f32_e32 v77, v76, v76
	v_add_f32_e32 v73, v81, v73
	v_add_f32_e32 v73, v77, v73
	global_store_dwordx4 v[78:79], v[64:67], off
	s_waitcnt vmcnt(15)
	v_lshlrev_b32_e32 v74, 16, v196
	v_and_b32_e32 v75, 0xffff0000, v196
	v_lshlrev_b32_e32 v68, 16, v197
	v_and_b32_e32 v69, 0xffff0000, v197
	v_lshlrev_b32_e32 v76, 16, v198
	v_and_b32_e32 v77, 0xffff0000, v198
	v_lshlrev_b32_e32 v70, 16, v199
	v_and_b32_e32 v71, 0xffff0000, v199
	v_pk_fma_f32 v[62:63], v[62:63], v[138:139], v[68:69] op_sel_hi:[1,0,1]
	v_pk_fma_f32 v[60:61], v[60:61], v[138:139], v[74:75] op_sel_hi:[1,0,1]
	v_pk_fma_f32 v[68:69], v[58:59], v[138:139], v[70:71] op_sel_hi:[1,0,1]
	v_pk_fma_f32 v[70:71], v[56:57], v[138:139], v[76:77] op_sel_hi:[1,0,1]
	v_mul_f32_e32 v56, v61, v61
	v_mul_f32_e32 v57, v63, v63
	v_mul_f32_e32 v58, v71, v71
	v_fmac_f32_e32 v56, v60, v60
	v_fmac_f32_e32 v57, v62, v62
	v_mul_f32_e32 v59, v69, v69
	v_fmac_f32_e32 v58, v70, v70
	v_add_f32_e32 v56, v56, v57
	v_add_f32_e32 v56, v58, v56
	v_fmac_f32_e32 v59, v68, v68
	v_add_f32_e32 v56, v59, v56
	v_add_f32_e32 v56, v73, v56
	ds_bpermute_b32 v57, v128, v56
	v_cvt_pk_bf16_f32 v58, v60, v61
	v_cvt_pk_bf16_f32 v59, v62, v63
	v_cvt_pk_bf16_f32 v60, v70, v71
	v_cvt_pk_bf16_f32 v61, v68, v69
	s_waitcnt lgkmcnt(0)
	v_add_f32_e32 v56, v56, v57
	ds_bpermute_b32 v57, v120, v56
	global_store_dwordx4 v[78:79], v[58:61], off offset:256
	s_and_saveexec_b64 s[2:3], vcc
	s_cbranch_execz .LBB0_266
	v_lshl_add_u32 v58, v72, 4, s5
	s_waitcnt lgkmcnt(0)
	v_add_f32_e32 v56, v56, v57
	ds_write_b32 v58, v56
; #define PG8_LAS __attribute__((address_space(3)))
; __device__ __forceinline__ unsigned cvt_pk_bf16(float lo, float hi) { unsigned r; asm volatile("v_cvt_pk_bf16_f32 %0, %1, %2" : "=v"(r) : "v"(lo), "v"(hi)); return r; }
;     __device__ __forceinline__ void khook(f32x4 (&acc)[2][2][4][2], int hb, int wr, int fr, PG8_LAS unsigned char* lds) const {
;     ...
;             for (int m = 0; m < 4; ++m) { const float r = RT[ai * HALF + m * 16];
; #pragma unroll
;                 for (int bj = 0; bj < 2; ++bj)
; #pragma unroll
;                     for (int n = 0; n < 2; ++n) acc[ai][bj][m][n] = acc[ai][bj][m][n] * r; } }
;     __device__ __forceinline__ void fused(f32x4 (&acc)[2][2][4][2], const Unit& u, int wr, int wc, int fr, int fq, PG8_LAS unsigned char* lds, int wid, int lane) const {
;         khook(acc, 0, wr, fr, lds);
;         PG8_LAS float* P = (PG8_LAS float*)lds;
;         const int col0 = u.pn * BM + wc * 32 + 8 * fq;
; #pragma unroll
;         for (int ai = 0; ai < 2; ++ai)
; #pragma unroll
;             for (int m = 0; m < 4; ++m) { const int rl = ai * HALF + wr * 64 + m * 16 + fr; const size_t off = (size_t)(u.pm * BM + rl) * ldc + col0; float q = 0.f;
; #pragma unroll
;                 for (int bj = 0; bj < 2; ++bj) { const u32x4 hb = *(const u32x4*)(xb + off + bj * HALF);
;                     const f32x4 b0 = (f32x4){__uint_as_float(hb.x << 16), __uint_as_float(hb.x & 0xffff0000u), __uint_as_float(hb.y << 16), __uint_as_float(hb.y & 0xffff0000u)};
;                     const f32x4 b1 = (f32x4){__uint_as_float(hb.z << 16), __uint_as_float(hb.z & 0xffff0000u), __uint_as_float(hb.w << 16), __uint_as_float(hb.w & 0xffff0000u)};
;                     const f32x4 v0 = b0 + acc[ai][bj][m][0], v1 = b1 + acc[ai][bj][m][1];
;                     u32x4 w; w.x = cvt_pk_bf16(v0[0], v0[1]); w.y = cvt_pk_bf16(v0[2], v0[3]); w.z = cvt_pk_bf16(v1[0], v1[1]); w.w = cvt_pk_bf16(v1[2], v1[3]);
;                     *(u32x4*)(xb + off + bj * HALF) = w;
;                     q += (v0[0] * v0[0] + v0[1] * v0[1]) + (v0[2] * v0[2] + v0[3] * v0[3]) + (v1[0] * v1[0] + v1[1] * v1[1]) + (v1[2] * v1[2] + v1[3] * v1[3]); }
;                 q += __shfl_xor(q, 16); q += __shfl_xor(q, 32);
;                 if (fq == 0) P[rl * 4 + wc] = q; }
.LBB0_266:
	s_or_b64 exec, exec, s[2:3]
	v_add_u32_e32 v56, 0x90, v144
	v_add_u32_e32 v58, s4, v56
	v_ashrrev_i32_e32 v59, 31, v58
	v_readlane_b32 s2, v252, 36
	v_lshlrev_b64 v[58:59], 12, v[58:59]
	v_readlane_b32 s3, v252, 37
	v_mov_b32_e32 v64, v139
	s_nop 0
	v_lshl_add_u64 v[58:59], s[2:3], 0, v[58:59]
	v_lshl_add_u64 v[62:63], v[2:3], 1, v[58:59]
	s_waitcnt vmcnt(15)
	v_lshlrev_b32_e32 v66, 16, v200
	v_and_b32_e32 v67, 0xffff0000, v200
	v_lshlrev_b32_e32 v58, 16, v201
	v_and_b32_e32 v59, 0xffff0000, v201
	v_lshlrev_b32_e32 v68, 16, v202
	v_and_b32_e32 v69, 0xffff0000, v202
	v_lshlrev_b32_e32 v60, 16, v203
	v_and_b32_e32 v61, 0xffff0000, v203
	v_pk_fma_f32 v[58:59], v[54:55], v[64:65], v[58:59] op_sel_hi:[1,0,1]
	v_pk_fma_f32 v[66:67], v[52:53], v[64:65], v[66:67] op_sel_hi:[1,0,1]
	v_pk_fma_f32 v[60:61], v[50:51], v[64:65], v[60:61] op_sel_hi:[1,0,1]
	v_pk_fma_f32 v[68:69], v[48:49], v[64:65], v[68:69] op_sel_hi:[1,0,1]
	v_cvt_pk_bf16_f32 v48, v66, v67
	v_cvt_pk_bf16_f32 v49, v58, v59
	s_waitcnt lgkmcnt(0)
	v_mul_f32_e32 v57, v67, v67
	v_cvt_pk_bf16_f32 v50, v68, v69
	v_cvt_pk_bf16_f32 v51, v60, v61
	v_mul_f32_e32 v59, v59, v59
	v_mul_f32_e32 v65, v69, v69
	v_fmac_f32_e32 v57, v66, v66
	v_fmac_f32_e32 v59, v58, v58
	v_mul_f32_e32 v61, v61, v61
	v_fmac_f32_e32 v65, v68, v68
	v_add_f32_e32 v57, v57, v59
	v_fmac_f32_e32 v61, v60, v60
	v_add_f32_e32 v57, v65, v57
	v_add_f32_e32 v57, v61, v57
	global_store_dwordx4 v[62:63], v[48:51], off
	s_waitcnt vmcnt(15)
	v_lshlrev_b32_e32 v58, 16, v204
	v_and_b32_e32 v59, 0xffff0000, v204
	v_lshlrev_b32_e32 v52, 16, v205
	v_and_b32_e32 v53, 0xffff0000, v205
	v_lshlrev_b32_e32 v60, 16, v206
	v_and_b32_e32 v61, 0xffff0000, v206
	v_lshlrev_b32_e32 v54, 16, v207
	v_and_b32_e32 v55, 0xffff0000, v207
	v_pk_fma_f32 v[46:47], v[46:47], v[64:65], v[52:53] op_sel_hi:[1,0,1]
	v_pk_fma_f32 v[44:45], v[44:45], v[64:65], v[58:59] op_sel_hi:[1,0,1]
	v_pk_fma_f32 v[52:53], v[42:43], v[64:65], v[54:55] op_sel_hi:[1,0,1]
	v_pk_fma_f32 v[54:55], v[40:41], v[64:65], v[60:61] op_sel_hi:[1,0,1]
	v_mul_f32_e32 v40, v45, v45
	v_mul_f32_e32 v41, v47, v47
	v_mul_f32_e32 v42, v55, v55
	v_fmac_f32_e32 v40, v44, v44
	v_fmac_f32_e32 v41, v46, v46
	v_mul_f32_e32 v43, v53, v53
	v_fmac_f32_e32 v42, v54, v54
	v_add_f32_e32 v40, v40, v41
	v_add_f32_e32 v40, v42, v40
	v_fmac_f32_e32 v43, v52, v52
	v_add_f32_e32 v40, v43, v40
	v_add_f32_e32 v40, v57, v40
	ds_bpermute_b32 v41, v128, v40
	v_cvt_pk_bf16_f32 v42, v44, v45
	v_cvt_pk_bf16_f32 v43, v46, v47
	v_cvt_pk_bf16_f32 v44, v54, v55
	v_cvt_pk_bf16_f32 v45, v52, v53
	s_waitcnt lgkmcnt(0)
	v_add_f32_e32 v40, v40, v41
	ds_bpermute_b32 v41, v120, v40
	global_store_dwordx4 v[62:63], v[42:45], off offset:256
	s_and_saveexec_b64 s[2:3], vcc
	s_cbranch_execz .LBB0_268
	v_lshl_add_u32 v42, v56, 4, s5
	s_waitcnt lgkmcnt(0)
	v_add_f32_e32 v40, v40, v41
	ds_write_b32 v42, v40
; #define PG8_LAS __attribute__((address_space(3)))
; __device__ __forceinline__ unsigned cvt_pk_bf16(float lo, float hi) { unsigned r; asm volatile("v_cvt_pk_bf16_f32 %0, %1, %2" : "=v"(r) : "v"(lo), "v"(hi)); return r; }
;     __device__ __forceinline__ void khook(f32x4 (&acc)[2][2][4][2], int hb, int wr, int fr, PG8_LAS unsigned char* lds) const {
;     ...
;             for (int m = 0; m < 4; ++m) { const float r = RT[ai * HALF + m * 16];
; #pragma unroll
;                 for (int bj = 0; bj < 2; ++bj)
; #pragma unroll
;                     for (int n = 0; n < 2; ++n) acc[ai][bj][m][n] = acc[ai][bj][m][n] * r; } }
;     __device__ __forceinline__ void fused(f32x4 (&acc)[2][2][4][2], const Unit& u, int wr, int wc, int fr, int fq, PG8_LAS unsigned char* lds, int wid, int lane) const {
;         khook(acc, 0, wr, fr, lds);
;         PG8_LAS float* P = (PG8_LAS float*)lds;
;         const int col0 = u.pn * BM + wc * 32 + 8 * fq;
; #pragma unroll
;         for (int ai = 0; ai < 2; ++ai)
; #pragma unroll
;             for (int m = 0; m < 4; ++m) { const int rl = ai * HALF + wr * 64 + m * 16 + fr; const size_t off = (size_t)(u.pm * BM + rl) * ldc + col0; float q = 0.f;
; #pragma unroll
;                 for (int bj = 0; bj < 2; ++bj) { const u32x4 hb = *(const u32x4*)(xb + off + bj * HALF);
;                     const f32x4 b0 = (f32x4){__uint_as_float(hb.x << 16), __uint_as_float(hb.x & 0xffff0000u), __uint_as_float(hb.y << 16), __uint_as_float(hb.y & 0xffff0000u)};
;                     const f32x4 b1 = (f32x4){__uint_as_float(hb.z << 16), __uint_as_float(hb.z & 0xffff0000u), __uint_as_float(hb.w << 16), __uint_as_float(hb.w & 0xffff0000u)};
;                     const f32x4 v0 = b0 + acc[ai][bj][m][0], v1 = b1 + acc[ai][bj][m][1];
;                     u32x4 w; w.x = cvt_pk_bf16(v0[0], v0[1]); w.y = cvt_pk_bf16(v0[2], v0[3]); w.z = cvt_pk_bf16(v1[0], v1[1]); w.w = cvt_pk_bf16(v1[2], v1[3]);
;                     *(u32x4*)(xb + off + bj * HALF) = w;
;                     q += (v0[0] * v0[0] + v0[1] * v0[1]) + (v0[2] * v0[2] + v0[3] * v0[3]) + (v1[0] * v1[0] + v1[1] * v1[1]) + (v1[2] * v1[2] + v1[3] * v1[3]); }
;                 q += __shfl_xor(q, 16); q += __shfl_xor(q, 32);
;                 if (fq == 0) P[rl * 4 + wc] = q; }
.LBB0_268:
	s_or_b64 exec, exec, s[2:3]
	v_add_u32_e32 v40, 0xa0, v144
	v_add_u32_e32 v42, s4, v40
	v_ashrrev_i32_e32 v43, 31, v42
	v_readlane_b32 s2, v252, 36
	v_lshlrev_b64 v[42:43], 12, v[42:43]
	v_readlane_b32 s3, v252, 37
	s_nop 1
	v_lshl_add_u64 v[42:43], s[2:3], 0, v[42:43]
	v_lshl_add_u64 v[46:47], v[2:3], 1, v[42:43]
	s_waitcnt vmcnt(15)
	v_lshlrev_b32_e32 v48, 16, v224
	v_and_b32_e32 v49, 0xffff0000, v224
	v_lshlrev_b32_e32 v42, 16, v225
	v_and_b32_e32 v43, 0xffff0000, v225
	v_lshlrev_b32_e32 v50, 16, v226
	v_and_b32_e32 v51, 0xffff0000, v226
	v_lshlrev_b32_e32 v44, 16, v227
	v_and_b32_e32 v45, 0xffff0000, v227
	v_pk_fma_f32 v[42:43], v[38:39], v[136:137], v[42:43] op_sel_hi:[1,0,1]
	v_pk_fma_f32 v[48:49], v[36:37], v[136:137], v[48:49] op_sel_hi:[1,0,1]
	v_pk_fma_f32 v[44:45], v[34:35], v[136:137], v[44:45] op_sel_hi:[1,0,1]
	v_pk_fma_f32 v[50:51], v[32:33], v[136:137], v[50:51] op_sel_hi:[1,0,1]
	v_cvt_pk_bf16_f32 v32, v48, v49
	v_cvt_pk_bf16_f32 v33, v42, v43
	s_waitcnt lgkmcnt(0)
	v_mul_f32_e32 v41, v49, v49
	v_cvt_pk_bf16_f32 v34, v50, v51
	v_cvt_pk_bf16_f32 v35, v44, v45
	v_mul_f32_e32 v43, v43, v43
	v_mul_f32_e32 v49, v51, v51
	v_fmac_f32_e32 v41, v48, v48
	v_fmac_f32_e32 v43, v42, v42
	v_mul_f32_e32 v45, v45, v45
	v_fmac_f32_e32 v49, v50, v50
	v_add_f32_e32 v41, v41, v43
	v_fmac_f32_e32 v45, v44, v44
	v_add_f32_e32 v41, v49, v41
	v_add_f32_e32 v41, v45, v41
	global_store_dwordx4 v[46:47], v[32:35], off
	s_waitcnt vmcnt(15)
	v_lshlrev_b32_e32 v42, 16, v228
	v_and_b32_e32 v43, 0xffff0000, v228
	v_lshlrev_b32_e32 v36, 16, v229
	v_and_b32_e32 v37, 0xffff0000, v229
	v_lshlrev_b32_e32 v44, 16, v230
	v_and_b32_e32 v45, 0xffff0000, v230
	v_lshlrev_b32_e32 v38, 16, v231
	v_and_b32_e32 v39, 0xffff0000, v231
	v_pk_fma_f32 v[30:31], v[30:31], v[136:137], v[36:37] op_sel_hi:[1,0,1]
	v_pk_fma_f32 v[28:29], v[28:29], v[136:137], v[42:43] op_sel_hi:[1,0,1]
	v_pk_fma_f32 v[36:37], v[26:27], v[136:137], v[38:39] op_sel_hi:[1,0,1]
	v_pk_fma_f32 v[38:39], v[24:25], v[136:137], v[44:45] op_sel_hi:[1,0,1]
	v_mul_f32_e32 v24, v29, v29
	v_mul_f32_e32 v25, v31, v31
	v_mul_f32_e32 v26, v39, v39
	v_fmac_f32_e32 v24, v28, v28
	v_fmac_f32_e32 v25, v30, v30
	v_mul_f32_e32 v27, v37, v37
	v_fmac_f32_e32 v26, v38, v38
	v_add_f32_e32 v24, v24, v25
	v_add_f32_e32 v24, v26, v24
	v_fmac_f32_e32 v27, v36, v36
	v_add_f32_e32 v24, v27, v24
	v_add_f32_e32 v24, v41, v24
	ds_bpermute_b32 v25, v128, v24
	v_cvt_pk_bf16_f32 v26, v28, v29
	v_cvt_pk_bf16_f32 v27, v30, v31
	v_cvt_pk_bf16_f32 v28, v38, v39
	v_cvt_pk_bf16_f32 v29, v36, v37
	s_waitcnt lgkmcnt(0)
	v_add_f32_e32 v24, v24, v25
	ds_bpermute_b32 v25, v120, v24
	global_store_dwordx4 v[46:47], v[26:29], off offset:256
	s_and_saveexec_b64 s[2:3], vcc
	s_cbranch_execz .LBB0_270
	v_lshl_add_u32 v26, v40, 4, s5
	s_waitcnt lgkmcnt(0)
	v_add_f32_e32 v24, v24, v25
	ds_write_b32 v26, v24
.LBB0_270:
	s_or_b64 exec, exec, s[2:3]
	v_add_u32_e32 v24, 0xb0, v144
	v_add_u32_e32 v26, s4, v24
	v_ashrrev_i32_e32 v27, 31, v26
	v_readlane_b32 s2, v252, 36
	v_lshlrev_b64 v[26:27], 12, v[26:27]
	v_readlane_b32 s3, v252, 37
	s_nop 1
	v_lshl_add_u64 v[26:27], s[2:3], 0, v[26:27]
	v_lshl_add_u64 v[30:31], v[2:3], 1, v[26:27]
	v_mov_b32_e32 v2, v137
	s_waitcnt vmcnt(15)
	v_lshlrev_b32_e32 v32, 16, v232
	v_and_b32_e32 v33, 0xffff0000, v232
	v_lshlrev_b32_e32 v26, 16, v233
	v_and_b32_e32 v27, 0xffff0000, v233
	v_lshlrev_b32_e32 v34, 16, v234
	v_and_b32_e32 v35, 0xffff0000, v234
	v_lshlrev_b32_e32 v28, 16, v235
	v_and_b32_e32 v29, 0xffff0000, v235
	v_pk_fma_f32 v[26:27], v[22:23], v[2:3], v[26:27] op_sel_hi:[1,0,1]
	v_pk_fma_f32 v[32:33], v[20:21], v[2:3], v[32:33] op_sel_hi:[1,0,1]
	v_pk_fma_f32 v[28:29], v[18:19], v[2:3], v[28:29] op_sel_hi:[1,0,1]
	v_pk_fma_f32 v[34:35], v[16:17], v[2:3], v[34:35] op_sel_hi:[1,0,1]
	v_cvt_pk_bf16_f32 v16, v32, v33
	v_cvt_pk_bf16_f32 v17, v26, v27
	v_mul_f32_e32 v3, v33, v33
	v_cvt_pk_bf16_f32 v18, v34, v35
	v_cvt_pk_bf16_f32 v19, v28, v29
	s_waitcnt lgkmcnt(0)
	v_mul_f32_e32 v25, v27, v27
	v_mul_f32_e32 v27, v35, v35
	v_fmac_f32_e32 v3, v32, v32
	v_fmac_f32_e32 v25, v26, v26
	v_mul_f32_e32 v29, v29, v29
	v_fmac_f32_e32 v27, v34, v34
	v_add_f32_e32 v3, v3, v25
	v_fmac_f32_e32 v29, v28, v28
	v_add_f32_e32 v3, v27, v3
	v_add_f32_e32 v3, v29, v3
	global_store_dwordx4 v[30:31], v[16:19], off
	s_waitcnt vmcnt(15)
	v_lshlrev_b32_e32 v26, 16, v236
	v_and_b32_e32 v27, 0xffff0000, v236
	v_lshlrev_b32_e32 v20, 16, v237
	v_and_b32_e32 v21, 0xffff0000, v237
	v_lshlrev_b32_e32 v28, 16, v238
	v_and_b32_e32 v29, 0xffff0000, v238
	v_lshlrev_b32_e32 v22, 16, v239
	v_and_b32_e32 v23, 0xffff0000, v239
	v_pk_fma_f32 v[14:15], v[14:15], v[2:3], v[20:21] op_sel_hi:[1,0,1]
	v_pk_fma_f32 v[12:13], v[12:13], v[2:3], v[26:27] op_sel_hi:[1,0,1]
	v_pk_fma_f32 v[20:21], v[10:11], v[2:3], v[22:23] op_sel_hi:[1,0,1]
	v_pk_fma_f32 v[10:11], v[8:9], v[2:3], v[28:29] op_sel_hi:[1,0,1]
	v_mul_f32_e32 v2, v13, v13
	v_mul_f32_e32 v8, v15, v15
	v_mul_f32_e32 v9, v11, v11
	v_fmac_f32_e32 v2, v12, v12
	v_fmac_f32_e32 v8, v14, v14
	v_mul_f32_e32 v22, v21, v21
	v_fmac_f32_e32 v9, v10, v10
	v_add_f32_e32 v2, v2, v8
	v_add_f32_e32 v2, v9, v2
	v_fmac_f32_e32 v22, v20, v20
	v_add_f32_e32 v2, v22, v2
	v_add_f32_e32 v2, v3, v2
	ds_bpermute_b32 v3, v128, v2
	v_cvt_pk_bf16_f32 v8, v12, v13
	v_cvt_pk_bf16_f32 v9, v14, v15
	v_cvt_pk_bf16_f32 v10, v10, v11
	v_cvt_pk_bf16_f32 v11, v20, v21
	s_waitcnt lgkmcnt(0)
	v_add_f32_e32 v2, v2, v3
	ds_bpermute_b32 v3, v120, v2
	global_store_dwordx4 v[30:31], v[8:11], off offset:256
	s_and_saveexec_b64 s[2:3], vcc
	s_cbranch_execz .LBB0_272
	v_lshl_add_u32 v8, v24, 4, s5
	s_waitcnt lgkmcnt(0)
	v_add_f32_e32 v2, v2, v3
	ds_write_b32 v8, v2

; #define PG8_LAS __attribute__((address_space(3)))
; #define PG8_WAIT_V(n) asm volatile("s_waitcnt vmcnt(" #n ")" ::: "memory")
; #define PG8_BAR __builtin_amdgcn_s_barrier()
;     __device__ __forceinline__ void fused(f32x4 (&acc)[2][2][4][2], const Unit& u, int wr, int wc, int fr, int fq, PG8_LAS unsigned char* lds, int wid, int lane) const {
;         PG8_LAS float* P = (PG8_LAS float*)lds;
;         PG8_LAS float* tbl = (PG8_LAS float*)(lds + 4096);
;         const int col0 = u.pn * BM + wc * 32 + 8 * fq;
; #pragma unroll
;         for (int ai = 0; ai < 2; ++ai)
; #pragma unroll
;             for (int m = 0; m < 4; ++m) { const int rl = ai * HALF + wr * 64 + m * 16 + fr; const size_t off = (size_t)(u.pm * BM + rl) * ldc + col0; float q = 0.f;
; #pragma unroll
;                 for (int bj = 0; bj < 2; ++bj) { const u32x4 hb = *(const u32x4*)(xb + off + bj * HALF);
;                     const f32x4 b0 = (f32x4){__uint_as_float(hb.x << 16), __uint_as_float(hb.x & 0xffff0000u), __uint_as_float(hb.y << 16), __uint_as_float(hb.y & 0xffff0000u)};
;                     const f32x4 b1 = (f32x4){__uint_as_float(hb.z << 16), __uint_as_float(hb.z & 0xffff0000u), __uint_as_float(hb.w << 16), __uint_as_float(hb.w & 0xffff0000u)};
;                     const f32x4 v0 = b0 + acc[ai][bj][m][0], v1 = b1 + acc[ai][bj][m][1]; acc[ai][bj][m][0] = v0; acc[ai][bj][m][1] = v1;
;                     q += (v0[0] * v0[0] + v0[1] * v0[1]) + (v0[2] * v0[2] + v0[3] * v0[3]) + (v1[0] * v1[0] + v1[1] * v1[1]) + (v1[2] * v1[2] + v1[3] * v1[3]); }
;                 q += __shfl_xor(q, 16); q += __shfl_xor(q, 32);
;                 if (fq == 0) P[rl * 4 + wc] = q; }
; template <class Epi, class Sched, bool ALIGN_EPI = false, bool SP2 = false>
; __device__ __forceinline__ void gemm_phase(PG8_LAS unsigned char* lds, const Gemm g, const Sched& S, const Epi& E) {
;     ...
;     PG8_WAIT_V(0);
;     if constexpr (!ALIGN_EPI) { if (wr == 0) PG8_BAR; }
;     PG8_BAR;
.LBB0_297:
	s_lshl_b32 s2, s72, 5
	s_lshl_b32 s3, s12, 8
	s_or_b32 s2, s3, s2
	s_lshl_b32 s3, s42, 8
	v_lshrrev_b32_e32 v208, 1, v150
	v_and_or_b32 v208, v208, 24, s2
	v_add_u32_e32 v209, s3, v149
	v_lshlrev_b32_e32 v209, 12, v209
	v_lshl_add_u32 v209, v208, 1, v209
	v_readlane_b32 s2, v252, 36
	v_readlane_b32 s3, v252, 37
	s_nop 4
	global_load_dwordx4 v[156:159], v209, s[2:3]
	global_load_dwordx4 v[160:163], v209, s[2:3] offset:256
	v_add_u32_e32 v209, 0x10000, v209
	global_load_dwordx4 v[164:167], v209, s[2:3]
	global_load_dwordx4 v[168:171], v209, s[2:3] offset:256
	v_add_u32_e32 v209, 0x10000, v209
	global_load_dwordx4 v[172:175], v209, s[2:3]
	global_load_dwordx4 v[176:179], v209, s[2:3] offset:256
	v_add_u32_e32 v209, 0x10000, v209
	global_load_dwordx4 v[184:187], v209, s[2:3]
	global_load_dwordx4 v[188:191], v209, s[2:3] offset:256
	v_add_u32_e32 v209, 0x50000, v209
	global_load_dwordx4 v[192:195], v209, s[2:3]
	global_load_dwordx4 v[196:199], v209, s[2:3] offset:256
	v_add_u32_e32 v209, 0x10000, v209
	global_load_dwordx4 v[200:203], v209, s[2:3]
	global_load_dwordx4 v[204:207], v209, s[2:3] offset:256
	v_add_u32_e32 v209, 0x10000, v209
	global_load_dwordx4 v[224:227], v209, s[2:3]
	global_load_dwordx4 v[228:231], v209, s[2:3] offset:256
	v_add_u32_e32 v209, 0x10000, v209
	global_load_dwordx4 v[232:235], v209, s[2:3]
	global_load_dwordx4 v[236:239], v209, s[2:3] offset:256
	s_waitcnt vmcnt(16)
	s_cmpk_lt_u32 s13, 0x100
	s_cselect_b64 s[6:7], -1, 0
	s_cmpk_gt_u32 s13, 0xff
	s_cbranch_scc1 .LBB0_299
	s_barrier
.LBB0_299:
	v_lshrrev_b32_e32 v2, 1, v150
	s_lshl_b32 s39, s72, 5
	s_lshl_b32 s0, s12, 8
	v_and_b32_e32 v140, 24, v2
	s_or_b32 s0, s0, s39
	s_lshl_b32 s38, s42, 8
	v_or_b32_e32 v2, s0, v140
	s_lshl_b32 s0, s72, 2
	v_add_u32_e32 v138, s38, v149
	s_add_i32 s2, s0, 0
	v_ashrrev_i32_e32 v139, 31, v138
	v_readlane_b32 s0, v252, 36
	v_lshlrev_b64 v[138:139], 12, v[138:139]
	v_readlane_b32 s1, v252, 37
	v_ashrrev_i32_e32 v3, 31, v2
	s_barrier
	v_lshl_add_u64 v[138:139], s[0:1], 0, v[138:139]
	v_lshl_add_u64 v[138:139], v[2:3], 1, v[138:139]
	v_and_b32_e32 v0, 63, v150
	v_cmp_lt_i32_e32 vcc, v219, v214
	s_waitcnt vmcnt(15)
	v_lshlrev_b32_e32 v146, 16, v156
	v_and_b32_e32 v147, 0xffff0000, v156
	v_lshlrev_b32_e32 v142, 16, v157
	v_and_b32_e32 v143, 0xffff0000, v157
	v_pk_add_f32 v[10:11], v[10:11], v[142:143]
	v_pk_add_f32 v[8:9], v[8:9], v[146:147]
	v_lshlrev_b32_e32 v150, 16, v158
	v_and_b32_e32 v151, 0xffff0000, v158
	v_mul_f32_e32 v141, v9, v9
	v_mul_f32_e32 v142, v11, v11
	v_pk_add_f32 v[12:13], v[12:13], v[150:151]
	v_fmac_f32_e32 v141, v8, v8
	v_fmac_f32_e32 v142, v10, v10
	v_lshlrev_b32_e32 v144, 16, v159
	v_and_b32_e32 v145, 0xffff0000, v159
	v_add_f32_e32 v141, v141, v142
	v_mul_f32_e32 v142, v13, v13
	v_pk_add_f32 v[14:15], v[14:15], v[144:145]
	v_fmac_f32_e32 v142, v12, v12
	v_add_f32_e32 v141, v142, v141
	v_mul_f32_e32 v142, v15, v15
	v_fmac_f32_e32 v142, v14, v14
	v_add_f32_e32 v141, v142, v141
	v_cndmask_b32_e32 v136, v213, v219, vcc
	v_lshlrev_b32_e32 v136, 2, v136
	v_cmp_lt_i32_e32 vcc, v220, v214
	s_waitcnt vmcnt(14)
	v_lshlrev_b32_e32 v138, 16, v160
	v_and_b32_e32 v139, 0xffff0000, v160
	v_lshlrev_b32_e32 v142, 16, v161
	v_and_b32_e32 v143, 0xffff0000, v161
	v_pk_add_f32 v[26:27], v[26:27], v[142:143]
	v_pk_add_f32 v[24:25], v[24:25], v[138:139]
	v_lshlrev_b32_e32 v146, 16, v162
	v_and_b32_e32 v147, 0xffff0000, v162
	v_mul_f32_e32 v138, v25, v25
	v_mul_f32_e32 v139, v27, v27
	v_pk_add_f32 v[28:29], v[28:29], v[146:147]
	v_fmac_f32_e32 v138, v24, v24
	v_fmac_f32_e32 v139, v26, v26
	v_lshlrev_b32_e32 v144, 16, v163
	v_and_b32_e32 v145, 0xffff0000, v163
	v_add_f32_e32 v138, v138, v139
	v_mul_f32_e32 v139, v29, v29
	v_pk_add_f32 v[30:31], v[30:31], v[144:145]
	v_fmac_f32_e32 v139, v28, v28
	v_add_f32_e32 v138, v139, v138
	v_mul_f32_e32 v139, v31, v31
	v_fmac_f32_e32 v139, v30, v30
	v_add_f32_e32 v138, v139, v138
	v_add_f32_e32 v138, v141, v138
	ds_bpermute_b32 v139, v136, v138
	v_cndmask_b32_e32 v137, v213, v220, vcc
	v_lshlrev_b32_e32 v137, 2, v137
	v_cmp_gt_u32_e32 vcc, 16, v0
	s_waitcnt lgkmcnt(0)
	v_add_f32_e32 v138, v138, v139
	ds_bpermute_b32 v139, v137, v138
	s_and_saveexec_b64 s[0:1], vcc
	s_movk_i32 s37, 0x2000
	s_cbranch_execz .LBB0_301
	v_lshl_add_u32 v141, v149, 4, s2
	s_waitcnt lgkmcnt(0)
	v_add_f32_e32 v138, v138, v139
	ds_write_b32 v141, v138
.LBB0_301:
	s_or_b64 exec, exec, s[0:1]
	v_or_b32_e32 v138, 16, v149
	v_add_u32_e32 v142, s38, v138
	v_ashrrev_i32_e32 v143, 31, v142
	v_readlane_b32 s0, v252, 36
	v_lshlrev_b64 v[142:143], 12, v[142:143]
	v_readlane_b32 s1, v252, 37
	s_nop 1
	v_lshl_add_u64 v[142:143], s[0:1], 0, v[142:143]
	v_lshl_add_u64 v[146:147], v[2:3], 1, v[142:143]
	s_waitcnt vmcnt(13)
	v_lshlrev_b32_e32 v150, 16, v164
	v_and_b32_e32 v151, 0xffff0000, v164
	v_lshlrev_b32_e32 v142, 16, v165
	v_and_b32_e32 v143, 0xffff0000, v165
	v_lshlrev_b32_e32 v152, 16, v166
	v_and_b32_e32 v153, 0xffff0000, v166
	v_lshlrev_b32_e32 v144, 16, v167
	v_and_b32_e32 v145, 0xffff0000, v167
	v_pk_add_f32 v[50:51], v[50:51], v[142:143]
	v_pk_add_f32 v[54:55], v[54:55], v[144:145]
	v_pk_add_f32 v[48:49], v[48:49], v[150:151]
	v_mul_f32_e32 v141, v51, v51
	s_waitcnt lgkmcnt(0)
	v_mul_f32_e32 v139, v49, v49
	v_pk_add_f32 v[52:53], v[52:53], v[152:153]
	v_fmac_f32_e32 v139, v48, v48
	v_fmac_f32_e32 v141, v50, v50
	v_add_f32_e32 v139, v139, v141
	v_mul_f32_e32 v141, v53, v53
	v_fmac_f32_e32 v141, v52, v52
	v_add_f32_e32 v139, v141, v139
	v_mul_f32_e32 v141, v55, v55
	v_fmac_f32_e32 v141, v54, v54
	v_add_f32_e32 v139, v141, v139
	s_waitcnt vmcnt(12)
	v_lshlrev_b32_e32 v146, 16, v168
	v_and_b32_e32 v147, 0xffff0000, v168
	v_lshlrev_b32_e32 v142, 16, v169
	v_and_b32_e32 v143, 0xffff0000, v169
	v_pk_add_f32 v[74:75], v[74:75], v[142:143]
	v_pk_add_f32 v[72:73], v[72:73], v[146:147]
	v_lshlrev_b32_e32 v150, 16, v170
	v_and_b32_e32 v151, 0xffff0000, v170
	v_mul_f32_e32 v141, v73, v73
	v_mul_f32_e32 v142, v75, v75
	v_pk_add_f32 v[76:77], v[76:77], v[150:151]
	v_fmac_f32_e32 v141, v72, v72
	v_fmac_f32_e32 v142, v74, v74
	v_lshlrev_b32_e32 v144, 16, v171
	v_and_b32_e32 v145, 0xffff0000, v171
	v_add_f32_e32 v141, v141, v142
	v_mul_f32_e32 v142, v77, v77
	v_pk_add_f32 v[78:79], v[78:79], v[144:145]
	v_fmac_f32_e32 v142, v76, v76
	v_add_f32_e32 v141, v142, v141
	v_mul_f32_e32 v142, v79, v79
	v_fmac_f32_e32 v142, v78, v78
	v_add_f32_e32 v141, v142, v141
	v_add_f32_e32 v139, v139, v141
	ds_bpermute_b32 v141, v136, v139
	s_waitcnt lgkmcnt(0)
	v_add_f32_e32 v139, v139, v141
	ds_bpermute_b32 v141, v137, v139
	s_and_saveexec_b64 s[0:1], vcc
	s_cbranch_execz .LBB0_303
	v_lshl_add_u32 v138, v138, 4, s2
	s_waitcnt lgkmcnt(0)
	v_add_f32_e32 v139, v139, v141
	ds_write_b32 v138, v139
;     __device__ __forceinline__ void fused(f32x4 (&acc)[2][2][4][2], const Unit& u, int wr, int wc, int fr, int fq, PG8_LAS unsigned char* lds, int wid, int lane) const {
;     ...
; #pragma unroll
;         for (int ai = 0; ai < 2; ++ai)
; #pragma unroll
;             for (int m = 0; m < 4; ++m) { const int rl = ai * HALF + wr * 64 + m * 16 + fr; const size_t off = (size_t)(u.pm * BM + rl) * ldc + col0; float q = 0.f;
; #pragma unroll
;                 for (int bj = 0; bj < 2; ++bj) { const u32x4 hb = *(const u32x4*)(xb + off + bj * HALF);
;                     const f32x4 b0 = (f32x4){__uint_as_float(hb.x << 16), __uint_as_float(hb.x & 0xffff0000u), __uint_as_float(hb.y << 16), __uint_as_float(hb.y & 0xffff0000u)};
;                     const f32x4 b1 = (f32x4){__uint_as_float(hb.z << 16), __uint_as_float(hb.z & 0xffff0000u), __uint_as_float(hb.w << 16), __uint_as_float(hb.w & 0xffff0000u)};
;                     const f32x4 v0 = b0 + acc[ai][bj][m][0], v1 = b1 + acc[ai][bj][m][1]; acc[ai][bj][m][0] = v0; acc[ai][bj][m][1] = v1;
;                     q += (v0[0] * v0[0] + v0[1] * v0[1]) + (v0[2] * v0[2] + v0[3] * v0[3]) + (v1[0] * v1[0] + v1[1] * v1[1]) + (v1[2] * v1[2] + v1[3] * v1[3]); }
;                 q += __shfl_xor(q, 16); q += __shfl_xor(q, 32);
;                 if (fq == 0) P[rl * 4 + wc] = q; }
.LBB0_303:
	s_or_b64 exec, exec, s[0:1]
	v_or_b32_e32 v138, 32, v149
	v_add_u32_e32 v142, s38, v138
	v_ashrrev_i32_e32 v143, 31, v142
	v_readlane_b32 s0, v252, 36
	v_lshlrev_b64 v[142:143], 12, v[142:143]
	v_readlane_b32 s1, v252, 37
	s_nop 1
	v_lshl_add_u64 v[142:143], s[0:1], 0, v[142:143]
	v_lshl_add_u64 v[146:147], v[2:3], 1, v[142:143]
	s_waitcnt vmcnt(11)
	v_lshlrev_b32_e32 v150, 16, v172
	v_and_b32_e32 v151, 0xffff0000, v172
	v_lshlrev_b32_e32 v142, 16, v173
	v_and_b32_e32 v143, 0xffff0000, v173
	v_lshlrev_b32_e32 v152, 16, v174
	v_and_b32_e32 v153, 0xffff0000, v174
	v_lshlrev_b32_e32 v144, 16, v175
	v_and_b32_e32 v145, 0xffff0000, v175
	v_pk_add_f32 v[98:99], v[98:99], v[142:143]
	v_pk_add_f32 v[102:103], v[102:103], v[144:145]
	v_pk_add_f32 v[96:97], v[96:97], v[150:151]
	s_waitcnt lgkmcnt(0)
	v_mul_f32_e32 v141, v99, v99
	v_mul_f32_e32 v139, v97, v97
	v_pk_add_f32 v[100:101], v[100:101], v[152:153]
	v_fmac_f32_e32 v139, v96, v96
	v_fmac_f32_e32 v141, v98, v98
	v_add_f32_e32 v139, v139, v141
	v_mul_f32_e32 v141, v101, v101
	v_fmac_f32_e32 v141, v100, v100
	v_add_f32_e32 v139, v141, v139
	v_mul_f32_e32 v141, v103, v103
	v_fmac_f32_e32 v141, v102, v102
	v_add_f32_e32 v139, v141, v139
	s_waitcnt vmcnt(10)
	v_lshlrev_b32_e32 v146, 16, v176
	v_and_b32_e32 v147, 0xffff0000, v176
	v_lshlrev_b32_e32 v142, 16, v177
	v_and_b32_e32 v143, 0xffff0000, v177
	v_pk_add_f32 v[114:115], v[114:115], v[142:143]
	v_pk_add_f32 v[112:113], v[112:113], v[146:147]
	v_lshlrev_b32_e32 v150, 16, v178
	v_and_b32_e32 v151, 0xffff0000, v178
	v_mul_f32_e32 v141, v113, v113
	v_mul_f32_e32 v142, v115, v115
	v_pk_add_f32 v[116:117], v[116:117], v[150:151]
	v_fmac_f32_e32 v141, v112, v112
	v_fmac_f32_e32 v142, v114, v114
	v_lshlrev_b32_e32 v144, 16, v179
	v_and_b32_e32 v145, 0xffff0000, v179
	v_add_f32_e32 v141, v141, v142
	v_mul_f32_e32 v142, v117, v117
	v_pk_add_f32 v[118:119], v[118:119], v[144:145]
	v_fmac_f32_e32 v142, v116, v116
	v_add_f32_e32 v141, v142, v141
	v_mul_f32_e32 v142, v119, v119
	v_fmac_f32_e32 v142, v118, v118
	v_add_f32_e32 v141, v142, v141
	v_add_f32_e32 v139, v139, v141
	ds_bpermute_b32 v141, v136, v139
	s_waitcnt lgkmcnt(0)
	v_add_f32_e32 v139, v139, v141
	ds_bpermute_b32 v141, v137, v139
	s_and_saveexec_b64 s[0:1], vcc
	s_cbranch_execz .LBB0_305
	v_lshl_add_u32 v138, v138, 4, s2
	s_waitcnt lgkmcnt(0)
	v_add_f32_e32 v139, v139, v141
	ds_write_b32 v138, v139
.LBB0_305:
	s_or_b64 exec, exec, s[0:1]
	v_or_b32_e32 v138, 48, v149
	v_add_u32_e32 v142, s38, v138
	v_ashrrev_i32_e32 v143, 31, v142
	v_readlane_b32 s0, v252, 36
	v_lshlrev_b64 v[142:143], 12, v[142:143]
	v_readlane_b32 s1, v252, 37
	s_nop 1
	v_lshl_add_u64 v[142:143], s[0:1], 0, v[142:143]
	v_lshl_add_u64 v[146:147], v[2:3], 1, v[142:143]
	s_waitcnt vmcnt(9)
	v_lshlrev_b32_e32 v150, 16, v184
	v_and_b32_e32 v151, 0xffff0000, v184
	v_lshlrev_b32_e32 v142, 16, v185
	v_and_b32_e32 v143, 0xffff0000, v185
	v_lshlrev_b32_e32 v152, 16, v186
	v_and_b32_e32 v153, 0xffff0000, v186
	v_lshlrev_b32_e32 v144, 16, v187
	v_and_b32_e32 v145, 0xffff0000, v187
	v_pk_add_f32 v[122:123], v[122:123], v[142:143]
	v_pk_add_f32 v[126:127], v[126:127], v[144:145]
	v_pk_add_f32 v[120:121], v[120:121], v[150:151]
	s_waitcnt lgkmcnt(0)
	v_mul_f32_e32 v141, v123, v123
	v_mul_f32_e32 v139, v121, v121
	v_pk_add_f32 v[124:125], v[124:125], v[152:153]
	v_fmac_f32_e32 v139, v120, v120
	v_fmac_f32_e32 v141, v122, v122
	v_add_f32_e32 v139, v139, v141
	v_mul_f32_e32 v141, v125, v125
	v_fmac_f32_e32 v141, v124, v124
	v_add_f32_e32 v139, v141, v139
	v_mul_f32_e32 v141, v127, v127
	v_fmac_f32_e32 v141, v126, v126
	v_add_f32_e32 v139, v141, v139
	s_waitcnt vmcnt(8)
	v_lshlrev_b32_e32 v146, 16, v188
	v_and_b32_e32 v147, 0xffff0000, v188
	v_lshlrev_b32_e32 v142, 16, v189
	v_and_b32_e32 v143, 0xffff0000, v189
	v_pk_add_f32 v[130:131], v[130:131], v[142:143]
	v_pk_add_f32 v[128:129], v[128:129], v[146:147]
	v_lshlrev_b32_e32 v150, 16, v190
	v_and_b32_e32 v151, 0xffff0000, v190
	v_mul_f32_e32 v141, v129, v129
	v_mul_f32_e32 v142, v131, v131
	v_pk_add_f32 v[132:133], v[132:133], v[150:151]
	v_fmac_f32_e32 v141, v128, v128
	v_fmac_f32_e32 v142, v130, v130
	v_lshlrev_b32_e32 v144, 16, v191
	v_and_b32_e32 v145, 0xffff0000, v191
	v_add_f32_e32 v141, v141, v142
	v_mul_f32_e32 v142, v133, v133
	v_pk_add_f32 v[134:135], v[134:135], v[144:145]
	v_fmac_f32_e32 v142, v132, v132
	v_add_f32_e32 v141, v142, v141
	v_mul_f32_e32 v142, v135, v135
	v_fmac_f32_e32 v142, v134, v134
	v_add_f32_e32 v141, v142, v141
	v_add_f32_e32 v139, v139, v141
	ds_bpermute_b32 v141, v136, v139
	s_waitcnt lgkmcnt(0)
	v_add_f32_e32 v139, v139, v141
	ds_bpermute_b32 v141, v137, v139
	s_and_saveexec_b64 s[0:1], vcc
	s_cbranch_execz .LBB0_307
	v_lshl_add_u32 v138, v138, 4, s2
	s_waitcnt lgkmcnt(0)
	v_add_f32_e32 v139, v139, v141
	ds_write_b32 v138, v139
;     __device__ __forceinline__ void fused(f32x4 (&acc)[2][2][4][2], const Unit& u, int wr, int wc, int fr, int fq, PG8_LAS unsigned char* lds, int wid, int lane) const {
;     ...
; #pragma unroll
;         for (int ai = 0; ai < 2; ++ai)
; #pragma unroll
;             for (int m = 0; m < 4; ++m) { const int rl = ai * HALF + wr * 64 + m * 16 + fr; const size_t off = (size_t)(u.pm * BM + rl) * ldc + col0; float q = 0.f;
; #pragma unroll
;                 for (int bj = 0; bj < 2; ++bj) { const u32x4 hb = *(const u32x4*)(xb + off + bj * HALF);
;                     const f32x4 b0 = (f32x4){__uint_as_float(hb.x << 16), __uint_as_float(hb.x & 0xffff0000u), __uint_as_float(hb.y << 16), __uint_as_float(hb.y & 0xffff0000u)};
;                     const f32x4 b1 = (f32x4){__uint_as_float(hb.z << 16), __uint_as_float(hb.z & 0xffff0000u), __uint_as_float(hb.w << 16), __uint_as_float(hb.w & 0xffff0000u)};
;                     const f32x4 v0 = b0 + acc[ai][bj][m][0], v1 = b1 + acc[ai][bj][m][1]; acc[ai][bj][m][0] = v0; acc[ai][bj][m][1] = v1;
;                     q += (v0[0] * v0[0] + v0[1] * v0[1]) + (v0[2] * v0[2] + v0[3] * v0[3]) + (v1[0] * v1[0] + v1[1] * v1[1]) + (v1[2] * v1[2] + v1[3] * v1[3]); }
;                 q += __shfl_xor(q, 16); q += __shfl_xor(q, 32);
;                 if (fq == 0) P[rl * 4 + wc] = q; }
.LBB0_307:
	s_or_b64 exec, exec, s[0:1]
	v_add_u32_e32 v138, 0x80, v149
	v_add_u32_e32 v142, s38, v138
	v_ashrrev_i32_e32 v143, 31, v142
	v_readlane_b32 s0, v252, 36
	v_lshlrev_b64 v[142:143], 12, v[142:143]
	v_readlane_b32 s1, v252, 37
	s_nop 1
	v_lshl_add_u64 v[142:143], s[0:1], 0, v[142:143]
	v_lshl_add_u64 v[146:147], v[2:3], 1, v[142:143]
	s_waitcnt vmcnt(7)
	v_lshlrev_b32_e32 v150, 16, v192
	v_and_b32_e32 v151, 0xffff0000, v192
	v_lshlrev_b32_e32 v142, 16, v193
	v_and_b32_e32 v143, 0xffff0000, v193
	v_lshlrev_b32_e32 v152, 16, v194
	v_and_b32_e32 v153, 0xffff0000, v194
	v_lshlrev_b32_e32 v144, 16, v195
	v_and_b32_e32 v145, 0xffff0000, v195
	v_pk_add_f32 v[18:19], v[18:19], v[142:143]
	v_pk_add_f32 v[22:23], v[22:23], v[144:145]
	v_pk_add_f32 v[16:17], v[16:17], v[150:151]
	s_waitcnt lgkmcnt(0)
	v_mul_f32_e32 v141, v19, v19
	v_mul_f32_e32 v139, v17, v17
	v_pk_add_f32 v[20:21], v[20:21], v[152:153]
	v_fmac_f32_e32 v139, v16, v16
	v_fmac_f32_e32 v141, v18, v18
	v_add_f32_e32 v139, v139, v141
	v_mul_f32_e32 v141, v21, v21
	v_fmac_f32_e32 v141, v20, v20
	v_add_f32_e32 v139, v141, v139
	v_mul_f32_e32 v141, v23, v23
	v_fmac_f32_e32 v141, v22, v22
	v_add_f32_e32 v139, v141, v139
	s_waitcnt vmcnt(6)
	v_lshlrev_b32_e32 v146, 16, v196
	v_and_b32_e32 v147, 0xffff0000, v196
	v_lshlrev_b32_e32 v142, 16, v197
	v_and_b32_e32 v143, 0xffff0000, v197
	v_pk_add_f32 v[42:43], v[42:43], v[142:143]
	v_pk_add_f32 v[40:41], v[40:41], v[146:147]
	v_lshlrev_b32_e32 v150, 16, v198
	v_and_b32_e32 v151, 0xffff0000, v198
	v_mul_f32_e32 v141, v41, v41
	v_mul_f32_e32 v142, v43, v43
	v_pk_add_f32 v[44:45], v[44:45], v[150:151]
	v_fmac_f32_e32 v141, v40, v40
	v_fmac_f32_e32 v142, v42, v42
	v_lshlrev_b32_e32 v144, 16, v199
	v_and_b32_e32 v145, 0xffff0000, v199
	v_add_f32_e32 v141, v141, v142
	v_mul_f32_e32 v142, v45, v45
	v_pk_add_f32 v[46:47], v[46:47], v[144:145]
	v_fmac_f32_e32 v142, v44, v44
	v_add_f32_e32 v141, v142, v141
	v_mul_f32_e32 v142, v47, v47
	v_fmac_f32_e32 v142, v46, v46
	v_add_f32_e32 v141, v142, v141
	v_add_f32_e32 v139, v139, v141
	ds_bpermute_b32 v141, v136, v139
	s_waitcnt lgkmcnt(0)
	v_add_f32_e32 v139, v139, v141
	ds_bpermute_b32 v141, v137, v139
	s_and_saveexec_b64 s[0:1], vcc
	s_cbranch_execz .LBB0_309
	v_lshl_add_u32 v138, v138, 4, s2
	s_waitcnt lgkmcnt(0)
	v_add_f32_e32 v139, v139, v141
	ds_write_b32 v138, v139
.LBB0_309:
	s_or_b64 exec, exec, s[0:1]
	v_add_u32_e32 v138, 0x90, v149
	v_add_u32_e32 v142, s38, v138
	v_ashrrev_i32_e32 v143, 31, v142
	v_readlane_b32 s0, v252, 36
	v_lshlrev_b64 v[142:143], 12, v[142:143]
	v_readlane_b32 s1, v252, 37
	s_nop 1
	v_lshl_add_u64 v[142:143], s[0:1], 0, v[142:143]
	v_lshl_add_u64 v[146:147], v[2:3], 1, v[142:143]
	s_waitcnt vmcnt(5)
	v_lshlrev_b32_e32 v150, 16, v200
	v_and_b32_e32 v151, 0xffff0000, v200
	v_lshlrev_b32_e32 v142, 16, v201
	v_and_b32_e32 v143, 0xffff0000, v201
	v_lshlrev_b32_e32 v152, 16, v202
	v_and_b32_e32 v153, 0xffff0000, v202
	v_lshlrev_b32_e32 v144, 16, v203
	v_and_b32_e32 v145, 0xffff0000, v203
	v_pk_add_f32 v[58:59], v[58:59], v[142:143]
	v_pk_add_f32 v[62:63], v[62:63], v[144:145]
	v_pk_add_f32 v[56:57], v[56:57], v[150:151]
	s_waitcnt lgkmcnt(0)
	v_mul_f32_e32 v141, v59, v59
	v_mul_f32_e32 v139, v57, v57
	v_pk_add_f32 v[60:61], v[60:61], v[152:153]
	v_fmac_f32_e32 v139, v56, v56
	v_fmac_f32_e32 v141, v58, v58
	v_add_f32_e32 v139, v139, v141
	v_mul_f32_e32 v141, v61, v61
	v_fmac_f32_e32 v141, v60, v60
	v_add_f32_e32 v139, v141, v139
	v_mul_f32_e32 v141, v63, v63
	v_fmac_f32_e32 v141, v62, v62
	v_add_f32_e32 v139, v141, v139
	s_waitcnt vmcnt(4)
	v_lshlrev_b32_e32 v146, 16, v204
	v_and_b32_e32 v147, 0xffff0000, v204
	v_lshlrev_b32_e32 v142, 16, v205
	v_and_b32_e32 v143, 0xffff0000, v205
	v_pk_add_f32 v[90:91], v[90:91], v[142:143]
	v_pk_add_f32 v[88:89], v[88:89], v[146:147]
	v_lshlrev_b32_e32 v150, 16, v206
	v_and_b32_e32 v151, 0xffff0000, v206
	v_mul_f32_e32 v141, v89, v89
	v_mul_f32_e32 v142, v91, v91
	v_pk_add_f32 v[92:93], v[92:93], v[150:151]
	v_fmac_f32_e32 v141, v88, v88
	v_fmac_f32_e32 v142, v90, v90
	v_lshlrev_b32_e32 v144, 16, v207
	v_and_b32_e32 v145, 0xffff0000, v207
	v_add_f32_e32 v141, v141, v142
	v_mul_f32_e32 v142, v93, v93
	v_pk_add_f32 v[94:95], v[94:95], v[144:145]
	v_fmac_f32_e32 v142, v92, v92
	v_add_f32_e32 v141, v142, v141
	v_mul_f32_e32 v142, v95, v95
	v_fmac_f32_e32 v142, v94, v94
	v_add_f32_e32 v141, v142, v141
	v_add_f32_e32 v139, v139, v141
	ds_bpermute_b32 v141, v136, v139
	s_waitcnt lgkmcnt(0)
	v_add_f32_e32 v139, v139, v141
	ds_bpermute_b32 v141, v137, v139
	s_and_saveexec_b64 s[0:1], vcc
	s_cbranch_execz .LBB0_311
	v_lshl_add_u32 v138, v138, 4, s2
	s_waitcnt lgkmcnt(0)
	v_add_f32_e32 v139, v139, v141
	ds_write_b32 v138, v139
;     __device__ __forceinline__ void fused(f32x4 (&acc)[2][2][4][2], const Unit& u, int wr, int wc, int fr, int fq, PG8_LAS unsigned char* lds, int wid, int lane) const {
;     ...
; #pragma unroll
;         for (int ai = 0; ai < 2; ++ai)
; #pragma unroll
;             for (int m = 0; m < 4; ++m) { const int rl = ai * HALF + wr * 64 + m * 16 + fr; const size_t off = (size_t)(u.pm * BM + rl) * ldc + col0; float q = 0.f;
; #pragma unroll
;                 for (int bj = 0; bj < 2; ++bj) { const u32x4 hb = *(const u32x4*)(xb + off + bj * HALF);
;                     const f32x4 b0 = (f32x4){__uint_as_float(hb.x << 16), __uint_as_float(hb.x & 0xffff0000u), __uint_as_float(hb.y << 16), __uint_as_float(hb.y & 0xffff0000u)};
;                     const f32x4 b1 = (f32x4){__uint_as_float(hb.z << 16), __uint_as_float(hb.z & 0xffff0000u), __uint_as_float(hb.w << 16), __uint_as_float(hb.w & 0xffff0000u)};
;                     const f32x4 v0 = b0 + acc[ai][bj][m][0], v1 = b1 + acc[ai][bj][m][1]; acc[ai][bj][m][0] = v0; acc[ai][bj][m][1] = v1;
;                     q += (v0[0] * v0[0] + v0[1] * v0[1]) + (v0[2] * v0[2] + v0[3] * v0[3]) + (v1[0] * v1[0] + v1[1] * v1[1]) + (v1[2] * v1[2] + v1[3] * v1[3]); }
;                 q += __shfl_xor(q, 16); q += __shfl_xor(q, 32);
;                 if (fq == 0) P[rl * 4 + wc] = q; }
.LBB0_311:
	s_or_b64 exec, exec, s[0:1]
	v_add_u32_e32 v138, 0xa0, v149
	v_add_u32_e32 v142, s38, v138
	v_ashrrev_i32_e32 v143, 31, v142
	v_readlane_b32 s0, v252, 36
	v_lshlrev_b64 v[142:143], 12, v[142:143]
	v_readlane_b32 s1, v252, 37
	s_nop 1
	v_lshl_add_u64 v[142:143], s[0:1], 0, v[142:143]
	v_lshl_add_u64 v[146:147], v[2:3], 1, v[142:143]
	s_waitcnt vmcnt(3)
	v_lshlrev_b32_e32 v150, 16, v224
	v_and_b32_e32 v151, 0xffff0000, v224
	v_lshlrev_b32_e32 v142, 16, v225
	v_and_b32_e32 v143, 0xffff0000, v225
	v_lshlrev_b32_e32 v152, 16, v226
	v_and_b32_e32 v153, 0xffff0000, v226
	v_lshlrev_b32_e32 v144, 16, v227
	v_and_b32_e32 v145, 0xffff0000, v227
	v_pk_add_f32 v[106:107], v[106:107], v[142:143]
	v_pk_add_f32 v[110:111], v[110:111], v[144:145]
	v_pk_add_f32 v[104:105], v[104:105], v[150:151]
	s_waitcnt lgkmcnt(0)
	v_mul_f32_e32 v141, v107, v107
	v_mul_f32_e32 v139, v105, v105
	v_pk_add_f32 v[108:109], v[108:109], v[152:153]
	v_fmac_f32_e32 v139, v104, v104
	v_fmac_f32_e32 v141, v106, v106
	v_add_f32_e32 v139, v139, v141
	v_mul_f32_e32 v141, v109, v109
	v_fmac_f32_e32 v141, v108, v108
	v_add_f32_e32 v139, v141, v139
	v_mul_f32_e32 v141, v111, v111
	v_fmac_f32_e32 v141, v110, v110
	v_add_f32_e32 v139, v141, v139
	s_waitcnt vmcnt(2)
	v_lshlrev_b32_e32 v146, 16, v228
	v_and_b32_e32 v147, 0xffff0000, v228
	v_lshlrev_b32_e32 v142, 16, v229
	v_and_b32_e32 v143, 0xffff0000, v229
	v_pk_add_f32 v[86:87], v[86:87], v[142:143]
	v_pk_add_f32 v[84:85], v[84:85], v[146:147]
	v_lshlrev_b32_e32 v150, 16, v230
	v_and_b32_e32 v151, 0xffff0000, v230
	v_mul_f32_e32 v141, v85, v85
	v_mul_f32_e32 v142, v87, v87
	v_pk_add_f32 v[80:81], v[80:81], v[150:151]
	v_fmac_f32_e32 v141, v84, v84
	v_fmac_f32_e32 v142, v86, v86
	v_lshlrev_b32_e32 v144, 16, v231
	v_and_b32_e32 v145, 0xffff0000, v231
	v_add_f32_e32 v141, v141, v142
	v_mul_f32_e32 v142, v81, v81
	v_pk_add_f32 v[82:83], v[82:83], v[144:145]
	v_fmac_f32_e32 v142, v80, v80
	v_add_f32_e32 v141, v142, v141
	v_mul_f32_e32 v142, v83, v83
	v_fmac_f32_e32 v142, v82, v82
	v_add_f32_e32 v141, v142, v141
	v_add_f32_e32 v139, v139, v141
	ds_bpermute_b32 v141, v136, v139
	s_waitcnt lgkmcnt(0)
	v_add_f32_e32 v139, v139, v141
	ds_bpermute_b32 v141, v137, v139
	s_and_saveexec_b64 s[0:1], vcc
	s_cbranch_execz .LBB0_313
	v_lshl_add_u32 v138, v138, 4, s2
	s_waitcnt lgkmcnt(0)
	v_add_f32_e32 v139, v139, v141
	ds_write_b32 v138, v139
.LBB0_313:
	s_or_b64 exec, exec, s[0:1]
	v_add_u32_e32 v138, 0xb0, v149
	v_add_u32_e32 v142, s38, v138
	v_ashrrev_i32_e32 v143, 31, v142
	v_readlane_b32 s0, v252, 36
	v_lshlrev_b64 v[142:143], 12, v[142:143]
	v_readlane_b32 s1, v252, 37
	s_nop 1
	v_lshl_add_u64 v[142:143], s[0:1], 0, v[142:143]
	v_lshl_add_u64 v[2:3], v[2:3], 1, v[142:143]
	s_waitcnt vmcnt(1)
	v_lshlrev_b32_e32 v146, 16, v232
	v_and_b32_e32 v147, 0xffff0000, v232
	v_lshlrev_b32_e32 v142, 16, v233
	v_and_b32_e32 v143, 0xffff0000, v233
	v_lshlrev_b32_e32 v150, 16, v234
	v_and_b32_e32 v151, 0xffff0000, v234
	v_lshlrev_b32_e32 v144, 16, v235
	v_and_b32_e32 v145, 0xffff0000, v235
	v_pk_add_f32 v[70:71], v[70:71], v[142:143]
	v_pk_add_f32 v[66:67], v[66:67], v[144:145]
	v_pk_add_f32 v[68:69], v[68:69], v[146:147]
	s_waitcnt lgkmcnt(0)
	v_mul_f32_e32 v141, v71, v71
	v_mul_f32_e32 v139, v69, v69
	v_pk_add_f32 v[64:65], v[64:65], v[150:151]
	v_fmac_f32_e32 v139, v68, v68
	v_fmac_f32_e32 v141, v70, v70
	v_add_f32_e32 v139, v139, v141
	v_mul_f32_e32 v141, v65, v65
	v_fmac_f32_e32 v141, v64, v64
	v_add_f32_e32 v139, v141, v139
	v_mul_f32_e32 v141, v67, v67
	v_fmac_f32_e32 v141, v66, v66
	v_add_f32_e32 v139, v141, v139
	s_waitcnt vmcnt(0)
	v_lshlrev_b32_e32 v2, 16, v236
	v_and_b32_e32 v3, 0xffff0000, v236
	v_lshlrev_b32_e32 v142, 16, v237
	v_and_b32_e32 v143, 0xffff0000, v237
	v_pk_add_f32 v[38:39], v[38:39], v[142:143]
	v_pk_add_f32 v[36:37], v[36:37], v[2:3]
	v_lshlrev_b32_e32 v146, 16, v238
	v_and_b32_e32 v147, 0xffff0000, v238
	v_mul_f32_e32 v2, v37, v37
	v_mul_f32_e32 v3, v39, v39
	v_pk_add_f32 v[32:33], v[32:33], v[146:147]
	v_fmac_f32_e32 v2, v36, v36
	v_fmac_f32_e32 v3, v38, v38
	v_lshlrev_b32_e32 v144, 16, v239
	v_and_b32_e32 v145, 0xffff0000, v239
	v_add_f32_e32 v2, v2, v3
	v_mul_f32_e32 v3, v33, v33
	v_pk_add_f32 v[34:35], v[34:35], v[144:145]
	v_fmac_f32_e32 v3, v32, v32
	v_add_f32_e32 v2, v3, v2
	v_mul_f32_e32 v3, v35, v35
	v_fmac_f32_e32 v3, v34, v34
	v_add_f32_e32 v2, v3, v2
	v_add_f32_e32 v2, v139, v2
	ds_bpermute_b32 v3, v136, v2
	s_waitcnt lgkmcnt(0)
	v_add_f32_e32 v2, v2, v3
	ds_bpermute_b32 v3, v137, v2
	s_and_saveexec_b64 s[0:1], vcc
	s_cbranch_execz .LBB0_315
	v_lshl_add_u32 v136, v138, 4, s2
	s_waitcnt lgkmcnt(0)
	v_add_f32_e32 v2, v2, v3
	ds_write_b32 v136, v2
